# v62 + 52 of the freed self-max issue slots deleted where no software hazard pair spans them (hazard-table checker over all CFG paths)
# speedup vs baseline: 1.0014x; 1.0014x over previous
.LBB0_658:
	s_barrier
	s_waitcnt vmcnt(11)
	ds_write_b128 v170, v[26:29]
	s_waitcnt vmcnt(10)
	ds_write_b128 v171, v[30:33]
	s_waitcnt vmcnt(9)
	ds_write_b128 v172, v[34:37] offset:17408
	s_waitcnt lgkmcnt(0)
	s_barrier
	ds_read_b128 v[106:109], v173
	ds_read_b128 v[134:137], v173 offset:8832
	ds_read_b128 v[114:117], v174
	s_waitcnt lgkmcnt(2)
	v_mfma_f32_16x16x32_bf16 v[110:113], v[106:109], v[2:5], 0
	s_add_i32 s45, s44, -3
	s_min_u32 s4, s45, s55
	s_lshl_b32 s4, s4, 6
	v_mfma_f32_16x16x32_bf16 v[106:109], v[106:109], v[14:17], 0
	s_addk_i32 s4, 0xff00
	s_and_b64 s[48:49], s[40:41], exec
	s_cselect_b32 s58, 0xc0, s4
	s_waitcnt lgkmcnt(0)
	v_mfma_f32_16x16x32_bf16 v[110:113], v[114:117], v[6:9], v[110:113]
	s_mul_i32 s52, s58, 0xc00
	s_lshl_b64 s[48:49], s[58:59], 11
	ds_read_b128 v[118:121], v174 offset:1088
	v_mfma_f32_16x16x32_bf16 v[106:109], v[114:117], v[18:21], v[106:109]
	ds_read_b128 v[114:117], v173 offset:128
	s_mul_hi_u32 s4, s58, 0xc00
	s_add_u32 s52, s42, s52
	s_waitcnt lgkmcnt(0)
	v_mfma_f32_16x16x32_bf16 v[122:125], v[114:117], v[10:13], v[110:113]
	s_nop 2
	ds_read_b128 v[110:113], v173 offset:1088
	ds_read_b128 v[130:133], v174 offset:8704
	s_addc_u32 s53, s43, s4
	v_lshl_add_u64 v[26:27], v[146:147], 1, s[52:53]
	v_lshl_add_u64 v[30:31], v[148:149], 1, s[52:53]
	v_lshl_add_u64 v[26:27], v[140:141], 1, v[26:27]
	v_lshl_add_u64 v[30:31], v[142:143], 1, v[30:31]
	v_lshl_add_u64 v[34:35], v[162:163], 0, s[48:49]
	global_load_dwordx4 v[26:29], v[26:27], off
	v_mfma_f32_16x16x32_bf16 v[106:109], v[114:117], v[22:25], v[106:109]
	global_load_dwordx4 v[30:33], v[30:31], off
	ds_read_b128 v[192:195], v174 offset:9792
	global_load_dwordx4 v[34:37], v[34:35], off
	s_waitcnt lgkmcnt(2)
	v_mfma_f32_16x16x32_bf16 v[114:117], v[110:113], v[2:5], 0
	s_nop 1
	v_max_f32_e32 v0, v124, v125
	v_mfma_f32_16x16x32_bf16 v[110:113], v[110:113], v[14:17], 0
	v_max3_f32 v0, v122, v123, v0
	v_mfma_f32_16x16x32_bf16 v[114:117], v[118:121], v[6:9], v[114:117]
	v_mfma_f32_16x16x32_bf16 v[110:113], v[118:121], v[18:21], v[110:113]
	ds_read_b128 v[118:121], v173 offset:1216
	s_waitcnt lgkmcnt(0)
	v_mfma_f32_16x16x32_bf16 v[126:129], v[118:121], v[10:13], v[114:117]
	s_nop 3
	ds_read_b128 v[114:117], v173 offset:8704
	s_nop 2
	s_nop 0
	v_mfma_f32_16x16x32_bf16 v[110:113], v[118:121], v[22:25], v[110:113]
	s_nop 0
	v_max_f32_e32 v164, v128, v129
	v_max3_f32 v164, v126, v127, v164
	s_waitcnt lgkmcnt(0)
	v_mfma_f32_16x16x32_bf16 v[118:121], v[114:117], v[2:5], 0
	v_max3_f32 v0, v0, s51, v164
	v_mfma_f32_16x16x32_bf16 v[114:117], v[114:117], v[14:17], 0
	v_mfma_f32_16x16x32_bf16 v[118:121], v[130:133], v[6:9], v[118:121]
	v_mfma_f32_16x16x32_bf16 v[114:117], v[130:133], v[18:21], v[114:117]
	v_mfma_f32_16x16x32_bf16 v[130:133], v[134:137], v[10:13], v[118:121]
	s_nop 5
	ds_read_b128 v[118:121], v173 offset:9792
	v_mfma_f32_16x16x32_bf16 v[114:117], v[134:137], v[22:25], v[114:117]
	s_nop 1
	v_max_f32_e32 v164, v132, v133
	s_waitcnt lgkmcnt(0)
	v_mfma_f32_16x16x32_bf16 v[134:137], v[118:121], v[2:5], 0
	v_max3_f32 v164, v130, v131, v164
	v_mfma_f32_16x16x32_bf16 v[118:121], v[118:121], v[14:17], 0
	v_mfma_f32_16x16x32_bf16 v[134:137], v[192:195], v[6:9], v[134:137]
	v_mfma_f32_16x16x32_bf16 v[118:121], v[192:195], v[18:21], v[118:121]
	ds_read_b128 v[192:195], v173 offset:9920
	s_waitcnt lgkmcnt(0)
	v_mfma_f32_16x16x32_bf16 v[134:137], v[192:195], v[10:13], v[134:137]
	s_nop 7
	s_nop 1
	v_max_f32_e32 v165, v136, v137
	v_max3_f32 v165, v134, v135, v165
	v_max3_f32 v0, v0, v164, v165
	ds_bpermute_b32 v164, v155, v0
	v_mfma_f32_16x16x32_bf16 v[118:121], v[192:195], v[22:25], v[118:121]
	s_waitcnt lgkmcnt(0)
	v_max_f32_e32 v0, v0, v164
	ds_bpermute_b32 v164, v176, v0
	s_waitcnt lgkmcnt(0)
	v_max_f32_e32 v0, v0, v164
	v_mul_f32_e32 v0, 0x3e16c740, v0
	v_add_f32_e32 v164, 0x41000000, v166
	v_cmp_gt_f32_e32 vcc, v0, v164
	s_cbranch_vccz .LBB0_660
	s_nop 0
	v_cndmask_b32_e32 v164, v166, v0, vcc
	v_sub_f32_e32 v0, v166, v164
	v_exp_f32_e32 v0, v0
	v_mov_b32_e32 v165, v167
	v_mov_b32_e32 v166, v164
	v_mul_f32_e32 v160, v160, v0
	v_pk_mul_f32 v[104:105], v[104:105], v[0:1] op_sel_hi:[1,0]
	v_pk_mul_f32 v[102:103], v[102:103], v[0:1] op_sel_hi:[1,0]
	v_pk_mul_f32 v[100:101], v[100:101], v[0:1] op_sel_hi:[1,0]
	v_pk_mul_f32 v[98:99], v[98:99], v[0:1] op_sel_hi:[1,0]
	v_pk_mul_f32 v[96:97], v[96:97], v[0:1] op_sel_hi:[1,0]
	v_pk_mul_f32 v[94:95], v[94:95], v[0:1] op_sel_hi:[1,0]
	v_pk_mul_f32 v[92:93], v[92:93], v[0:1] op_sel_hi:[1,0]
	v_pk_mul_f32 v[90:91], v[90:91], v[0:1] op_sel_hi:[1,0]
	s_branch .LBB0_661

.LBB0_661:
	v_fma_f32 v0, v122, s46, -v166
	v_exp_f32_e32 v122, v0
	v_fma_f32 v0, v123, s46, -v166
	v_exp_f32_e32 v168, v0
	v_fma_f32 v0, v124, s46, -v166
	v_exp_f32_e32 v123, v0
	v_fma_f32 v0, v125, s46, -v166
	v_exp_f32_e32 v169, v0
	v_fma_f32 v0, v126, s46, -v166
	v_exp_f32_e32 v124, v0
	v_fma_f32 v0, v127, s46, -v166
	v_exp_f32_e32 v192, v0
	v_fma_f32 v0, v128, s46, -v166
	v_exp_f32_e32 v125, v0
	v_fma_f32 v0, v129, s46, -v166
	v_exp_f32_e32 v193, v0
	v_add_f32_e32 v126, v122, v168
	v_add_f32_e32 v127, v123, v169
	s_nop 0
	v_add_f32_e32 v0, v126, v127
	v_add_f32_e32 v126, v124, v192
	v_add_f32_e32 v127, v125, v193
	v_add_f32_e32 v167, 0, v0
	v_add_f32_e32 v194, v126, v126
	v_add_f32_e32 v195, v126, v127
	v_fma_f32 v126, v131, s46, -v166
	v_exp_f32_e32 v177, v126
	v_fma_f32 v126, v132, s46, -v166
	v_exp_f32_e32 v179, v126
	v_fma_f32 v126, v133, s46, -v166
	v_exp_f32_e32 v196, v126
	v_fma_f32 v126, v134, s46, -v166
	v_fma_f32 v0, v130, s46, -v166
	v_exp_f32_e32 v130, v126
	v_fma_f32 v126, v135, s46, -v166
	v_exp_f32_e32 v132, v126
	v_fma_f32 v126, v136, s46, -v166
	v_exp_f32_e32 v0, v0
	v_exp_f32_e32 v194, v126
	v_fma_f32 v126, v137, s46, -v166
	v_exp_f32_e32 v166, v126
	v_add_f32_e32 v131, v0, v177
	v_add_f32_e32 v133, v179, v196
	v_add_f32_e32 v126, v130, v132
	v_add_f32_e32 v127, v131, v133
	v_add_f32_e32 v128, v194, v166
	v_add_f32_e32 v129, v195, v167
	s_nop 0
	v_add_f32_e32 v126, v126, v128
	v_add_f32_e32 v127, v127, v129
	s_nop 0
	v_add_f32_e32 v126, v126, v127
	ds_bpermute_b32 v127, v155, v126
	s_waitcnt lgkmcnt(0)
	v_add_f32_e32 v126, v126, v127
	ds_bpermute_b32 v127, v176, v126
	s_waitcnt lgkmcnt(0)
	v_add_f32_e32 v126, v126, v127
	v_add_f32_e32 v160, v160, v126
	v_max_f32_e32 v126, v108, v109
	v_max_f32_e32 v127, v112, v113
	v_max3_f32 v126, v106, v107, v126
	v_max3_f32 v127, v110, v111, v127
	v_max3_f32 v126, v126, s51, v127
	v_max_f32_e32 v127, v116, v117
	v_max_f32_e32 v128, v120, v121
	v_max3_f32 v127, v114, v115, v127
	v_max3_f32 v128, v118, v119, v128
	v_max3_f32 v131, v126, v127, v128
	ds_bpermute_b32 v133, v155, v131
	v_cvt_pk_bf16_f32 v126, v122, v168
	v_cvt_pk_bf16_f32 v127, v123, v169
	v_cvt_pk_bf16_f32 v128, v124, v192
	v_cvt_pk_bf16_f32 v129, v125, v193
	s_waitcnt lgkmcnt(0)
	v_max_f32_e32 v131, v131, v133
	ds_bpermute_b32 v133, v176, v131
	v_cvt_pk_bf16_f32 v122, v0, v177
	v_cvt_pk_bf16_f32 v123, v179, v196
	v_cvt_pk_bf16_f32 v124, v130, v132
	v_add_f32_e32 v130, 0x41000000, v165
	s_waitcnt lgkmcnt(0)
	v_max_f32_e32 v0, v131, v133
	v_mul_f32_e32 v0, 0x3e16c740, v0
	v_cmp_gt_f32_e32 vcc, v0, v130
	v_cvt_pk_bf16_f32 v125, v194, v166
	s_cbranch_vccz .LBB0_663
	s_nop 0
	v_cndmask_b32_e32 v130, v165, v0, vcc
	v_sub_f32_e32 v0, v165, v130
	v_exp_f32_e32 v0, v0
	v_mov_b32_e32 v165, v130
	v_mul_f32_e32 v161, v161, v0
	v_pk_mul_f32 v[88:89], v[88:89], v[0:1] op_sel_hi:[1,0]
	v_pk_mul_f32 v[86:87], v[86:87], v[0:1] op_sel_hi:[1,0]
	v_pk_mul_f32 v[84:85], v[84:85], v[0:1] op_sel_hi:[1,0]
	v_pk_mul_f32 v[82:83], v[82:83], v[0:1] op_sel_hi:[1,0]
	v_pk_mul_f32 v[80:81], v[80:81], v[0:1] op_sel_hi:[1,0]
	v_pk_mul_f32 v[78:79], v[78:79], v[0:1] op_sel_hi:[1,0]
	v_pk_mul_f32 v[76:77], v[76:77], v[0:1] op_sel_hi:[1,0]
	v_pk_mul_f32 v[74:75], v[74:75], v[0:1] op_sel_hi:[1,0]
.LBB0_663:
	v_fma_f32 v0, v106, s46, -v165
	v_exp_f32_e32 v106, v0
	v_fma_f32 v0, v107, s46, -v165
	v_exp_f32_e32 v130, v0
	v_fma_f32 v0, v108, s46, -v165
	v_exp_f32_e32 v107, v0
	v_fma_f32 v0, v109, s46, -v165
	v_exp_f32_e32 v131, v0
	v_fma_f32 v0, v110, s46, -v165
	v_exp_f32_e32 v108, v0
	v_fma_f32 v0, v111, s46, -v165
	v_exp_f32_e32 v110, v0
	v_fma_f32 v0, v112, s46, -v165
	v_exp_f32_e32 v109, v0
	v_fma_f32 v0, v113, s46, -v165
	v_exp_f32_e32 v111, v0
	v_add_f32_e32 v112, v106, v130
	v_add_f32_e32 v113, v107, v131
	v_mov_b64_e32 v[168:169], v[164:165]
	v_add_f32_e32 v0, v112, v113
	v_add_f32_e32 v112, v108, v110
	v_add_f32_e32 v113, v109, v111
	v_add_f32_e32 v133, 0, v0
	v_add_f32_e32 v134, v112, v112
	v_add_f32_e32 v135, v112, v113
	v_fma_f32 v112, v115, s46, -v165
	v_exp_f32_e32 v136, v112
	v_fma_f32 v112, v116, s46, -v165
	v_fma_f32 v113, v119, s46, -v165
	v_fma_f32 v0, v114, s46, -v165
	v_exp_f32_e32 v137, v112
	v_fma_f32 v112, v117, s46, -v165
	v_exp_f32_e32 v114, v113
	v_fma_f32 v113, v120, s46, -v165
	v_exp_f32_e32 v0, v0
	v_exp_f32_e32 v164, v112
	v_fma_f32 v112, v118, s46, -v165
	v_exp_f32_e32 v134, v113
	v_fma_f32 v113, v121, s46, -v165
	v_exp_f32_e32 v112, v112
	v_exp_f32_e32 v132, v113
	v_add_f32_e32 v113, v0, v136
	v_add_f32_e32 v115, v137, v164
	v_add_f32_e32 v116, v112, v114
	v_add_f32_e32 v117, v113, v115
	v_add_f32_e32 v118, v134, v132
	v_add_f32_e32 v119, v135, v133
	v_cvt_pk_bf16_f32 v106, v106, v130
	v_cvt_pk_bf16_f32 v107, v107, v131
	v_cvt_pk_bf16_f32 v108, v108, v110
	v_cvt_pk_bf16_f32 v109, v109, v111
	v_cvt_pk_bf16_f32 v110, v0, v136
	s_nop 0
	v_add_f32_e32 v116, v116, v118
	v_add_f32_e32 v117, v117, v119
	v_cvt_pk_bf16_f32 v111, v137, v164
	v_cvt_pk_bf16_f32 v112, v112, v114
	s_nop 0
	v_add_f32_e32 v113, v116, v117
	ds_bpermute_b32 v115, v155, v113
	s_waitcnt lgkmcnt(0)
	v_add_f32_e32 v113, v113, v115
	ds_bpermute_b32 v115, v176, v113
	s_waitcnt lgkmcnt(0)
	v_add_f32_e32 v113, v113, v115
	v_add_f32_e32 v161, v161, v113
	v_cvt_pk_bf16_f32 v113, v134, v132
	ds_read_b64_tr_b16 v[116:117], v175 offset:18560
	ds_read_b64_tr_b16 v[114:115], v175 offset:17408
	ds_read_b64_tr_b16 v[118:119], v175 offset:17440
	ds_read_b64_tr_b16 v[120:121], v175 offset:18592
	s_waitcnt lgkmcnt(2)
	v_mfma_f32_16x16x32_bf16 v[102:105], v[114:117], v[126:129], v[102:105]
	v_mfma_f32_16x16x32_bf16 v[114:117], v[114:117], v[106:109], v[86:89]
	s_waitcnt lgkmcnt(0)
	v_mfma_f32_16x16x32_bf16 v[98:101], v[118:121], v[126:129], v[98:101]
	v_mfma_f32_16x16x32_bf16 v[118:121], v[118:121], v[106:109], v[82:85]
	s_nop 2
	ds_read_b64_tr_b16 v[82:83], v175 offset:17472
	ds_read_b64_tr_b16 v[84:85], v175 offset:18624
	s_waitcnt lgkmcnt(0)
	v_mfma_f32_16x16x32_bf16 v[130:133], v[82:85], v[106:109], v[78:81]
	s_nop 2
	ds_read_b64_tr_b16 v[78:79], v175 offset:17504
	ds_read_b64_tr_b16 v[80:81], v175 offset:18656
	v_mfma_f32_16x16x32_bf16 v[94:97], v[82:85], v[126:129], v[94:97]
	s_waitcnt lgkmcnt(0)
	v_mfma_f32_16x16x32_bf16 v[90:93], v[78:81], v[126:129], v[90:93]
	v_mfma_f32_16x16x32_bf16 v[106:109], v[78:81], v[106:109], v[74:77]
	s_nop 2
	ds_read_b64_tr_b16 v[76:77], v175 offset:27776
	ds_read_b64_tr_b16 v[74:75], v175 offset:26624
	ds_read_b64_tr_b16 v[78:79], v175 offset:26656
	ds_read_b64_tr_b16 v[80:81], v175 offset:27808
	s_add_i32 s4, s44, -2
	s_min_u32 s4, s4, s55
	s_waitcnt lgkmcnt(2)
	v_mfma_f32_16x16x32_bf16 v[86:89], v[74:77], v[122:125], v[102:105]
	s_lshl_b32 s4, s4, 6
	s_addk_i32 s4, 0xff00
	s_and_b64 s[48:49], s[40:41], exec
	v_mfma_f32_16x16x32_bf16 v[102:105], v[74:77], v[110:113], v[114:117]
	ds_read_b64_tr_b16 v[74:75], v175 offset:26688
	ds_read_b64_tr_b16 v[76:77], v175 offset:27840
	s_nop 0
	ds_read_b64_tr_b16 v[114:115], v175 offset:26720
	ds_read_b64_tr_b16 v[116:117], v175 offset:27872
	s_waitcnt lgkmcnt(0)
	v_mfma_f32_16x16x32_bf16 v[82:85], v[78:81], v[122:125], v[98:101]
	s_barrier
	s_waitcnt vmcnt(11)
	ds_write_b128 v170, v[38:41]
	s_waitcnt vmcnt(10)
	ds_write_b128 v171, v[42:45]
	s_waitcnt vmcnt(9)
	ds_write_b128 v172, v[46:49] offset:17408
	v_mfma_f32_16x16x32_bf16 v[98:101], v[78:81], v[110:113], v[118:121]
	s_waitcnt lgkmcnt(0)
	s_barrier
	v_mfma_f32_16x16x32_bf16 v[78:81], v[74:77], v[122:125], v[94:97]
	ds_read_b128 v[134:137], v173 offset:8832
	s_cselect_b32 s58, 0xc0, s4
	s_mul_i32 s52, s58, 0xc00
	v_mfma_f32_16x16x32_bf16 v[94:97], v[74:77], v[110:113], v[130:133]
	s_lshl_b64 s[48:49], s[58:59], 11
	ds_read_b128 v[118:121], v174 offset:1088
	s_mul_hi_u32 s4, s58, 0xc00
	v_mfma_f32_16x16x32_bf16 v[74:77], v[114:117], v[122:125], v[90:93]
	s_add_u32 s52, s42, s52
	s_addc_u32 s53, s43, s4
	v_lshl_add_u64 v[38:39], v[146:147], 1, s[52:53]
	v_mfma_f32_16x16x32_bf16 v[90:93], v[114:117], v[110:113], v[106:109]
	ds_read_b128 v[114:117], v174
	v_lshl_add_u64 v[42:43], v[148:149], 1, s[52:53]
	v_lshl_add_u64 v[38:39], v[140:141], 1, v[38:39]
	ds_read_b128 v[106:109], v173
	s_waitcnt lgkmcnt(0)
	v_mfma_f32_16x16x32_bf16 v[110:113], v[106:109], v[2:5], 0
	v_lshl_add_u64 v[42:43], v[142:143], 1, v[42:43]
	v_lshl_add_u64 v[46:47], v[162:163], 0, s[48:49]
	global_load_dwordx4 v[38:41], v[38:39], off
	v_mfma_f32_16x16x32_bf16 v[106:109], v[106:109], v[14:17], 0
	global_load_dwordx4 v[42:45], v[42:43], off
	ds_read_b128 v[130:133], v174 offset:8704
	global_load_dwordx4 v[46:49], v[46:47], off
	v_mfma_f32_16x16x32_bf16 v[110:113], v[114:117], v[6:9], v[110:113]
	ds_read_b128 v[192:195], v174 offset:9792
	v_mfma_f32_16x16x32_bf16 v[106:109], v[114:117], v[18:21], v[106:109]
	ds_read_b128 v[114:117], v173 offset:128
	s_waitcnt lgkmcnt(0)
	v_mfma_f32_16x16x32_bf16 v[122:125], v[114:117], v[10:13], v[110:113]
	s_nop 2
	ds_read_b128 v[110:113], v173 offset:1088
	s_nop 3
	s_nop 0
	v_mfma_f32_16x16x32_bf16 v[106:109], v[114:117], v[22:25], v[106:109]
	s_nop 0
	v_max_f32_e32 v0, v124, v125
	v_max3_f32 v0, v122, v123, v0
	s_waitcnt lgkmcnt(0)
	v_mfma_f32_16x16x32_bf16 v[114:117], v[110:113], v[2:5], 0
	v_mfma_f32_16x16x32_bf16 v[110:113], v[110:113], v[14:17], 0
	v_mfma_f32_16x16x32_bf16 v[114:117], v[118:121], v[6:9], v[114:117]
	v_mfma_f32_16x16x32_bf16 v[110:113], v[118:121], v[18:21], v[110:113]
	ds_read_b128 v[118:121], v173 offset:1216
	s_waitcnt lgkmcnt(0)
	v_mfma_f32_16x16x32_bf16 v[126:129], v[118:121], v[10:13], v[114:117]
	s_nop 3
	ds_read_b128 v[114:117], v173 offset:8704
	s_nop 2
	s_nop 0
	v_mfma_f32_16x16x32_bf16 v[110:113], v[118:121], v[22:25], v[110:113]
	s_nop 0
	v_max_f32_e32 v164, v128, v129
	v_max3_f32 v164, v126, v127, v164
	s_waitcnt lgkmcnt(0)
	v_mfma_f32_16x16x32_bf16 v[118:121], v[114:117], v[2:5], 0
	v_max3_f32 v0, v0, s51, v164
	v_mfma_f32_16x16x32_bf16 v[114:117], v[114:117], v[14:17], 0
	v_mfma_f32_16x16x32_bf16 v[118:121], v[130:133], v[6:9], v[118:121]
	v_mfma_f32_16x16x32_bf16 v[114:117], v[130:133], v[18:21], v[114:117]
	v_mfma_f32_16x16x32_bf16 v[130:133], v[134:137], v[10:13], v[118:121]
	s_nop 5
	ds_read_b128 v[118:121], v173 offset:9792
	v_mfma_f32_16x16x32_bf16 v[114:117], v[134:137], v[22:25], v[114:117]
	s_nop 1
	v_max_f32_e32 v164, v132, v133
	s_waitcnt lgkmcnt(0)
	v_mfma_f32_16x16x32_bf16 v[134:137], v[118:121], v[2:5], 0
	v_max3_f32 v164, v130, v131, v164
	v_mfma_f32_16x16x32_bf16 v[118:121], v[118:121], v[14:17], 0
	v_mfma_f32_16x16x32_bf16 v[134:137], v[192:195], v[6:9], v[134:137]
	v_mfma_f32_16x16x32_bf16 v[118:121], v[192:195], v[18:21], v[118:121]
	ds_read_b128 v[192:195], v173 offset:9920
	s_waitcnt lgkmcnt(0)
	v_mfma_f32_16x16x32_bf16 v[134:137], v[192:195], v[10:13], v[134:137]
	s_nop 7
	s_nop 1
	v_max_f32_e32 v166, v136, v137
	v_max3_f32 v166, v134, v135, v166
	v_max3_f32 v0, v0, v164, v166
	ds_bpermute_b32 v164, v155, v0
	v_mfma_f32_16x16x32_bf16 v[118:121], v[192:195], v[22:25], v[118:121]
	s_waitcnt lgkmcnt(0)
	v_max_f32_e32 v0, v0, v164
	ds_bpermute_b32 v164, v176, v0
	s_waitcnt lgkmcnt(0)
	v_max_f32_e32 v0, v0, v164
	v_mul_f32_e32 v0, 0x3e16c740, v0
	v_add_f32_e32 v164, 0x41000000, v168
	v_cmp_gt_f32_e32 vcc, v0, v164
	s_cbranch_vccz .LBB0_665
	s_nop 0
	v_cndmask_b32_e32 v166, v168, v0, vcc
	v_sub_f32_e32 v0, v168, v166
	v_exp_f32_e32 v0, v0
	v_mov_b32_e32 v167, v169
	v_mov_b32_e32 v165, v169
	v_mov_b32_e32 v168, v166
	v_mul_f32_e32 v160, v160, v0
	v_pk_mul_f32 v[88:89], v[88:89], v[0:1] op_sel_hi:[1,0]
	v_pk_mul_f32 v[86:87], v[86:87], v[0:1] op_sel_hi:[1,0]
	v_pk_mul_f32 v[84:85], v[84:85], v[0:1] op_sel_hi:[1,0]
	v_pk_mul_f32 v[82:83], v[82:83], v[0:1] op_sel_hi:[1,0]
	v_pk_mul_f32 v[80:81], v[80:81], v[0:1] op_sel_hi:[1,0]
	v_pk_mul_f32 v[78:79], v[78:79], v[0:1] op_sel_hi:[1,0]
	v_pk_mul_f32 v[76:77], v[76:77], v[0:1] op_sel_hi:[1,0]
	v_pk_mul_f32 v[74:75], v[74:75], v[0:1] op_sel_hi:[1,0]
	s_branch .LBB0_666

.LBB0_666:
	v_fma_f32 v0, v122, s46, -v168
	v_exp_f32_e32 v122, v0
	v_fma_f32 v0, v123, s46, -v168
	v_exp_f32_e32 v192, v0
	v_fma_f32 v0, v124, s46, -v168
	v_exp_f32_e32 v123, v0
	v_fma_f32 v0, v125, s46, -v168
	v_exp_f32_e32 v193, v0
	v_fma_f32 v0, v126, s46, -v168
	v_exp_f32_e32 v124, v0
	v_fma_f32 v0, v127, s46, -v168
	v_exp_f32_e32 v194, v0
	v_fma_f32 v0, v128, s46, -v168
	v_exp_f32_e32 v125, v0
	v_fma_f32 v0, v129, s46, -v168
	v_exp_f32_e32 v195, v0
	v_add_f32_e32 v126, v122, v192
	v_add_f32_e32 v127, v123, v193
	s_nop 0
	v_add_f32_e32 v0, v126, v127
	v_add_f32_e32 v126, v124, v194
	v_add_f32_e32 v127, v125, v195
	v_add_f32_e32 v169, 0, v0
	v_add_f32_e32 v196, v126, v126
	v_add_f32_e32 v197, v126, v127
	v_fma_f32 v126, v131, s46, -v168
	v_exp_f32_e32 v164, v126
	v_fma_f32 v126, v132, s46, -v168
	v_exp_f32_e32 v177, v126
	v_fma_f32 v126, v133, s46, -v168
	v_exp_f32_e32 v179, v126
	v_fma_f32 v126, v134, s46, -v168
	v_fma_f32 v0, v130, s46, -v168
	v_exp_f32_e32 v130, v126
	v_fma_f32 v126, v135, s46, -v168
	v_exp_f32_e32 v132, v126
	v_fma_f32 v126, v136, s46, -v168
	v_exp_f32_e32 v0, v0
	v_exp_f32_e32 v196, v126
	v_fma_f32 v126, v137, s46, -v168
	v_exp_f32_e32 v168, v126
	v_add_f32_e32 v131, v0, v164
	v_add_f32_e32 v133, v177, v179
	v_add_f32_e32 v126, v130, v132
	v_add_f32_e32 v127, v131, v133
	v_add_f32_e32 v128, v196, v168
	v_add_f32_e32 v129, v197, v169
	s_nop 0
	v_add_f32_e32 v126, v126, v128
	v_add_f32_e32 v127, v127, v129
	s_nop 0
	v_add_f32_e32 v126, v126, v127
	ds_bpermute_b32 v127, v155, v126
	s_waitcnt lgkmcnt(0)
	v_add_f32_e32 v126, v126, v127
	ds_bpermute_b32 v127, v176, v126
	s_waitcnt lgkmcnt(0)
	v_add_f32_e32 v126, v126, v127
	v_add_f32_e32 v160, v160, v126
	v_max_f32_e32 v126, v108, v109
	v_max_f32_e32 v127, v112, v113
	v_max3_f32 v126, v106, v107, v126
	v_max3_f32 v127, v110, v111, v127
	v_max3_f32 v126, v126, s51, v127
	v_max_f32_e32 v127, v116, v117
	v_max_f32_e32 v128, v120, v121
	v_max3_f32 v127, v114, v115, v127
	v_max3_f32 v128, v118, v119, v128
	v_max3_f32 v131, v126, v127, v128
	ds_bpermute_b32 v133, v155, v131
	v_cvt_pk_bf16_f32 v126, v122, v192
	v_cvt_pk_bf16_f32 v127, v123, v193
	v_cvt_pk_bf16_f32 v128, v124, v194
	v_cvt_pk_bf16_f32 v129, v125, v195
	s_waitcnt lgkmcnt(0)
	v_max_f32_e32 v131, v131, v133
	ds_bpermute_b32 v133, v176, v131
	v_cvt_pk_bf16_f32 v122, v0, v164
	v_cvt_pk_bf16_f32 v123, v177, v179
	v_cvt_pk_bf16_f32 v124, v130, v132
	v_add_f32_e32 v130, 0x41000000, v165
	s_waitcnt lgkmcnt(0)
	v_max_f32_e32 v0, v131, v133
	v_mul_f32_e32 v0, 0x3e16c740, v0
	v_cmp_gt_f32_e32 vcc, v0, v130
	v_cvt_pk_bf16_f32 v125, v196, v168
	s_cbranch_vccz .LBB0_668
	s_nop 0
	v_cndmask_b32_e32 v167, v165, v0, vcc
	v_sub_f32_e32 v0, v165, v167
	v_exp_f32_e32 v0, v0
	v_mov_b32_e32 v165, v167
	v_mul_f32_e32 v161, v161, v0
	v_pk_mul_f32 v[104:105], v[104:105], v[0:1] op_sel_hi:[1,0]
	v_pk_mul_f32 v[102:103], v[102:103], v[0:1] op_sel_hi:[1,0]
	v_pk_mul_f32 v[100:101], v[100:101], v[0:1] op_sel_hi:[1,0]
	v_pk_mul_f32 v[98:99], v[98:99], v[0:1] op_sel_hi:[1,0]
	v_pk_mul_f32 v[96:97], v[96:97], v[0:1] op_sel_hi:[1,0]
	v_pk_mul_f32 v[94:95], v[94:95], v[0:1] op_sel_hi:[1,0]
	v_pk_mul_f32 v[92:93], v[92:93], v[0:1] op_sel_hi:[1,0]
	v_pk_mul_f32 v[90:91], v[90:91], v[0:1] op_sel_hi:[1,0]
.LBB0_668:
	v_fma_f32 v0, v106, s46, -v165
	v_exp_f32_e32 v106, v0
	v_fma_f32 v0, v107, s46, -v165
	v_exp_f32_e32 v130, v0
	v_fma_f32 v0, v108, s46, -v165
	v_exp_f32_e32 v107, v0
	v_fma_f32 v0, v109, s46, -v165
	v_exp_f32_e32 v131, v0
	v_fma_f32 v0, v110, s46, -v165
	v_exp_f32_e32 v108, v0
	v_fma_f32 v0, v111, s46, -v165
	v_exp_f32_e32 v110, v0
	v_fma_f32 v0, v112, s46, -v165
	v_exp_f32_e32 v109, v0
	v_fma_f32 v0, v113, s46, -v165
	v_exp_f32_e32 v111, v0
	v_add_f32_e32 v112, v106, v130
	v_add_f32_e32 v113, v107, v131
	v_cvt_pk_bf16_f32 v106, v106, v130
	v_cvt_pk_bf16_f32 v107, v107, v131
	s_nop 0
	v_add_f32_e32 v0, v112, v113
	v_add_f32_e32 v112, v108, v110
	v_add_f32_e32 v113, v109, v111
	v_add_f32_e32 v133, 0, v0
	v_add_f32_e32 v134, v112, v112
	v_add_f32_e32 v135, v112, v113
	v_fma_f32 v112, v115, s46, -v165
	v_exp_f32_e32 v136, v112
	v_fma_f32 v112, v116, s46, -v165
	v_fma_f32 v113, v119, s46, -v165
	v_fma_f32 v0, v114, s46, -v165
	v_exp_f32_e32 v137, v112
	v_fma_f32 v112, v117, s46, -v165
	v_exp_f32_e32 v114, v113
	v_fma_f32 v113, v120, s46, -v165
	v_exp_f32_e32 v0, v0
	v_exp_f32_e32 v164, v112
	v_fma_f32 v112, v118, s46, -v165
	v_exp_f32_e32 v134, v113
	v_fma_f32 v113, v121, s46, -v165
	v_exp_f32_e32 v112, v112
	v_exp_f32_e32 v132, v113
	v_add_f32_e32 v113, v0, v136
	v_add_f32_e32 v115, v137, v164
	v_add_f32_e32 v116, v112, v114
	v_add_f32_e32 v117, v113, v115
	v_add_f32_e32 v118, v134, v132
	v_add_f32_e32 v119, v135, v133
	v_cvt_pk_bf16_f32 v108, v108, v110
	v_cvt_pk_bf16_f32 v109, v109, v111
	v_cvt_pk_bf16_f32 v110, v0, v136
	v_cvt_pk_bf16_f32 v111, v137, v164
	v_cvt_pk_bf16_f32 v112, v112, v114
	s_nop 0
	v_add_f32_e32 v116, v116, v118
	v_add_f32_e32 v117, v117, v119
	s_nop 0
	v_add_f32_e32 v113, v116, v117
	ds_bpermute_b32 v115, v155, v113
	s_waitcnt lgkmcnt(0)
	v_add_f32_e32 v113, v113, v115
	ds_bpermute_b32 v115, v176, v113
	s_waitcnt lgkmcnt(0)
	v_add_f32_e32 v113, v113, v115
	v_add_f32_e32 v161, v161, v113
	v_cvt_pk_bf16_f32 v113, v134, v132
	ds_read_b64_tr_b16 v[116:117], v175 offset:18560
	ds_read_b64_tr_b16 v[114:115], v175 offset:17408
	ds_read_b64_tr_b16 v[118:119], v175 offset:17440
	ds_read_b64_tr_b16 v[120:121], v175 offset:18592
	s_waitcnt lgkmcnt(2)
	v_mfma_f32_16x16x32_bf16 v[86:89], v[114:117], v[126:129], v[86:89]
	v_mfma_f32_16x16x32_bf16 v[102:105], v[114:117], v[106:109], v[102:105]
	ds_read_b64_tr_b16 v[114:115], v175 offset:17472
	ds_read_b64_tr_b16 v[116:117], v175 offset:18624
	s_waitcnt lgkmcnt(0)
	v_mfma_f32_16x16x32_bf16 v[78:81], v[114:117], v[126:129], v[78:81]
	v_mfma_f32_16x16x32_bf16 v[94:97], v[114:117], v[106:109], v[94:97]
	ds_read_b64_tr_b16 v[114:115], v175 offset:17504
	ds_read_b64_tr_b16 v[116:117], v175 offset:18656
	v_mfma_f32_16x16x32_bf16 v[82:85], v[118:121], v[126:129], v[82:85]
	v_mfma_f32_16x16x32_bf16 v[98:101], v[118:121], v[106:109], v[98:101]
	s_waitcnt lgkmcnt(0)
	v_mfma_f32_16x16x32_bf16 v[74:77], v[114:117], v[126:129], v[74:77]
	v_mfma_f32_16x16x32_bf16 v[90:93], v[114:117], v[106:109], v[90:93]
	ds_read_b64_tr_b16 v[108:109], v175 offset:27776
	ds_read_b64_tr_b16 v[106:107], v175 offset:26624
	ds_read_b64_tr_b16 v[114:115], v175 offset:26656
	ds_read_b64_tr_b16 v[116:117], v175 offset:27808
	s_add_i32 s4, s44, -1
	s_min_u32 s4, s4, s55
	s_waitcnt lgkmcnt(2)
	v_mfma_f32_16x16x32_bf16 v[86:89], v[106:109], v[122:125], v[86:89]
	s_lshl_b32 s4, s4, 6
	s_addk_i32 s4, 0xff00
	s_and_b64 s[48:49], s[40:41], exec
	v_mfma_f32_16x16x32_bf16 v[102:105], v[106:109], v[110:113], v[102:105]
	ds_read_b64_tr_b16 v[106:107], v175 offset:26688
	ds_read_b64_tr_b16 v[108:109], v175 offset:27840
	s_cselect_b32 s58, 0xc0, s4
	s_mul_i32 s52, s58, 0xc00
	s_waitcnt lgkmcnt(0)
	v_mfma_f32_16x16x32_bf16 v[78:81], v[106:109], v[122:125], v[78:81]
	s_lshl_b64 s[48:49], s[58:59], 11
	s_mul_hi_u32 s4, s58, 0xc00
	s_add_u32 s52, s42, s52
	v_mfma_f32_16x16x32_bf16 v[94:97], v[106:109], v[110:113], v[94:97]
	ds_read_b64_tr_b16 v[106:107], v175 offset:26720
	ds_read_b64_tr_b16 v[108:109], v175 offset:27872
	s_waitcnt lgkmcnt(0)
	s_barrier
	v_mfma_f32_16x16x32_bf16 v[74:77], v[106:109], v[122:125], v[74:77]
	s_waitcnt vmcnt(11)
	ds_write_b128 v170, v[50:53]
	s_waitcnt vmcnt(10)
	ds_write_b128 v171, v[54:57]
	s_waitcnt vmcnt(9)
	ds_write_b128 v172, v[58:61] offset:17408
	s_waitcnt lgkmcnt(0)
	v_mfma_f32_16x16x32_bf16 v[90:93], v[106:109], v[110:113], v[90:93]
	s_barrier
	ds_read_b128 v[106:109], v173
	ds_read_b128 v[134:137], v173 offset:8832
	v_mfma_f32_16x16x32_bf16 v[82:85], v[114:117], v[122:125], v[82:85]
	ds_read_b128 v[118:121], v174 offset:1088
	s_addc_u32 s53, s43, s4
	v_lshl_add_u64 v[50:51], v[146:147], 1, s[52:53]
	v_mfma_f32_16x16x32_bf16 v[98:101], v[114:117], v[110:113], v[98:101]
	ds_read_b128 v[114:117], v174
	v_lshl_add_u64 v[54:55], v[148:149], 1, s[52:53]
	v_lshl_add_u64 v[50:51], v[140:141], 1, v[50:51]
	s_waitcnt lgkmcnt(3)
	v_mfma_f32_16x16x32_bf16 v[110:113], v[106:109], v[2:5], 0
	v_lshl_add_u64 v[54:55], v[142:143], 1, v[54:55]
	v_lshl_add_u64 v[58:59], v[162:163], 0, s[48:49]
	global_load_dwordx4 v[50:53], v[50:51], off
	v_mfma_f32_16x16x32_bf16 v[106:109], v[106:109], v[14:17], 0
	global_load_dwordx4 v[54:57], v[54:55], off
	ds_read_b128 v[130:133], v174 offset:8704
	global_load_dwordx4 v[58:61], v[58:59], off
	s_waitcnt lgkmcnt(1)
	v_mfma_f32_16x16x32_bf16 v[110:113], v[114:117], v[6:9], v[110:113]
	ds_read_b128 v[192:195], v174 offset:9792
	v_mfma_f32_16x16x32_bf16 v[106:109], v[114:117], v[18:21], v[106:109]
	ds_read_b128 v[114:117], v173 offset:128
	s_waitcnt lgkmcnt(0)
	v_mfma_f32_16x16x32_bf16 v[122:125], v[114:117], v[10:13], v[110:113]
	s_nop 2
	ds_read_b128 v[110:113], v173 offset:1088
	s_nop 3
	s_nop 0
	v_mfma_f32_16x16x32_bf16 v[106:109], v[114:117], v[22:25], v[106:109]
	s_nop 0
	v_max_f32_e32 v0, v124, v125
	v_max3_f32 v0, v122, v123, v0
	s_waitcnt lgkmcnt(0)
	v_mfma_f32_16x16x32_bf16 v[114:117], v[110:113], v[2:5], 0
	v_mfma_f32_16x16x32_bf16 v[110:113], v[110:113], v[14:17], 0
	v_mfma_f32_16x16x32_bf16 v[114:117], v[118:121], v[6:9], v[114:117]
	v_mfma_f32_16x16x32_bf16 v[110:113], v[118:121], v[18:21], v[110:113]
	ds_read_b128 v[118:121], v173 offset:1216
	s_waitcnt lgkmcnt(0)
	v_mfma_f32_16x16x32_bf16 v[126:129], v[118:121], v[10:13], v[114:117]
	s_nop 3
	ds_read_b128 v[114:117], v173 offset:8704
	s_nop 2
	s_nop 0
	v_mfma_f32_16x16x32_bf16 v[110:113], v[118:121], v[22:25], v[110:113]
	s_nop 0
	v_max_f32_e32 v164, v128, v129
	v_max3_f32 v164, v126, v127, v164
	s_waitcnt lgkmcnt(0)
	v_mfma_f32_16x16x32_bf16 v[118:121], v[114:117], v[2:5], 0
	v_max3_f32 v0, v0, s51, v164
	v_mfma_f32_16x16x32_bf16 v[114:117], v[114:117], v[14:17], 0
	v_mfma_f32_16x16x32_bf16 v[118:121], v[130:133], v[6:9], v[118:121]
	v_mfma_f32_16x16x32_bf16 v[114:117], v[130:133], v[18:21], v[114:117]
	v_mfma_f32_16x16x32_bf16 v[130:133], v[134:137], v[10:13], v[118:121]
	s_nop 5
	ds_read_b128 v[118:121], v173 offset:9792
	v_mfma_f32_16x16x32_bf16 v[114:117], v[134:137], v[22:25], v[114:117]
	s_nop 1
	v_max_f32_e32 v164, v132, v133
	s_waitcnt lgkmcnt(0)
	v_mfma_f32_16x16x32_bf16 v[134:137], v[118:121], v[2:5], 0
	v_max3_f32 v164, v130, v131, v164
	v_mfma_f32_16x16x32_bf16 v[118:121], v[118:121], v[14:17], 0
	v_mfma_f32_16x16x32_bf16 v[134:137], v[192:195], v[6:9], v[134:137]
	v_mfma_f32_16x16x32_bf16 v[118:121], v[192:195], v[18:21], v[118:121]
	ds_read_b128 v[192:195], v173 offset:9920
	s_waitcnt lgkmcnt(0)
	v_mfma_f32_16x16x32_bf16 v[134:137], v[192:195], v[10:13], v[134:137]
	s_nop 7
	s_nop 1
	v_max_f32_e32 v168, v136, v137
	v_max3_f32 v168, v134, v135, v168
	v_max3_f32 v0, v0, v164, v168
	ds_bpermute_b32 v164, v155, v0
	v_mfma_f32_16x16x32_bf16 v[118:121], v[192:195], v[22:25], v[118:121]
	s_waitcnt lgkmcnt(0)
	v_max_f32_e32 v0, v0, v164
	ds_bpermute_b32 v164, v176, v0
	s_waitcnt lgkmcnt(0)
	v_max_f32_e32 v0, v0, v164
	v_mul_f32_e32 v0, 0x3e16c740, v0
	v_add_f32_e32 v164, 0x41000000, v166
	v_cmp_gt_f32_e32 vcc, v0, v164
	s_cbranch_vccz .LBB0_670
	s_nop 0
	v_cndmask_b32_e32 v168, v166, v0, vcc
	v_sub_f32_e32 v0, v166, v168
	v_exp_f32_e32 v0, v0
	v_mov_b32_e32 v169, v167
	v_mov_b32_e32 v165, v167
	v_mov_b32_e32 v166, v168
	v_mul_f32_e32 v160, v160, v0
	v_pk_mul_f32 v[88:89], v[88:89], v[0:1] op_sel_hi:[1,0]
	v_pk_mul_f32 v[86:87], v[86:87], v[0:1] op_sel_hi:[1,0]
	v_pk_mul_f32 v[84:85], v[84:85], v[0:1] op_sel_hi:[1,0]
	v_pk_mul_f32 v[82:83], v[82:83], v[0:1] op_sel_hi:[1,0]
	v_pk_mul_f32 v[80:81], v[80:81], v[0:1] op_sel_hi:[1,0]
	v_pk_mul_f32 v[78:79], v[78:79], v[0:1] op_sel_hi:[1,0]
	v_pk_mul_f32 v[76:77], v[76:77], v[0:1] op_sel_hi:[1,0]
	v_pk_mul_f32 v[74:75], v[74:75], v[0:1] op_sel_hi:[1,0]
	s_branch .LBB0_671

.LBB0_671:
	v_fma_f32 v0, v122, s46, -v166
	v_exp_f32_e32 v122, v0
	v_fma_f32 v0, v123, s46, -v166
	v_exp_f32_e32 v192, v0
	v_fma_f32 v0, v124, s46, -v166
	v_exp_f32_e32 v123, v0
	v_fma_f32 v0, v125, s46, -v166
	v_exp_f32_e32 v193, v0
	v_fma_f32 v0, v126, s46, -v166
	v_exp_f32_e32 v124, v0
	v_fma_f32 v0, v127, s46, -v166
	v_exp_f32_e32 v194, v0
	v_fma_f32 v0, v128, s46, -v166
	v_exp_f32_e32 v125, v0
	v_fma_f32 v0, v129, s46, -v166
	v_exp_f32_e32 v195, v0
	v_add_f32_e32 v126, v122, v192
	v_add_f32_e32 v127, v123, v193
	s_nop 0
	v_add_f32_e32 v0, v126, v127
	v_add_f32_e32 v126, v124, v194
	v_add_f32_e32 v127, v125, v195
	v_add_f32_e32 v167, 0, v0
	v_add_f32_e32 v196, v126, v126
	v_add_f32_e32 v197, v126, v127
	v_fma_f32 v126, v131, s46, -v166
	v_exp_f32_e32 v164, v126
	v_fma_f32 v126, v132, s46, -v166
	v_exp_f32_e32 v177, v126
	v_fma_f32 v126, v133, s46, -v166
	v_exp_f32_e32 v179, v126
	v_fma_f32 v126, v134, s46, -v166
	v_fma_f32 v0, v130, s46, -v166
	v_exp_f32_e32 v130, v126
	v_fma_f32 v126, v135, s46, -v166
	v_exp_f32_e32 v132, v126
	v_fma_f32 v126, v136, s46, -v166
	v_exp_f32_e32 v0, v0
	v_exp_f32_e32 v196, v126
	v_fma_f32 v126, v137, s46, -v166
	v_exp_f32_e32 v166, v126
	v_add_f32_e32 v131, v0, v164
	v_add_f32_e32 v133, v177, v179
	v_add_f32_e32 v126, v130, v132
	v_add_f32_e32 v127, v131, v133
	v_add_f32_e32 v128, v196, v166
	v_add_f32_e32 v129, v197, v167
	s_nop 0
	v_add_f32_e32 v126, v126, v128
	v_add_f32_e32 v127, v127, v129
	s_nop 0
	v_add_f32_e32 v126, v126, v127
	ds_bpermute_b32 v127, v155, v126
	s_waitcnt lgkmcnt(0)
	v_add_f32_e32 v126, v126, v127
	ds_bpermute_b32 v127, v176, v126
	s_waitcnt lgkmcnt(0)
	v_add_f32_e32 v126, v126, v127
	v_add_f32_e32 v160, v160, v126
	v_max_f32_e32 v126, v108, v109
	v_max_f32_e32 v127, v112, v113
	v_max3_f32 v126, v106, v107, v126
	v_max3_f32 v127, v110, v111, v127
	v_max3_f32 v126, v126, s51, v127
	v_max_f32_e32 v127, v116, v117
	v_max_f32_e32 v128, v120, v121
	v_max3_f32 v127, v114, v115, v127
	v_max3_f32 v128, v118, v119, v128
	v_max3_f32 v131, v126, v127, v128
	ds_bpermute_b32 v133, v155, v131
	v_cvt_pk_bf16_f32 v126, v122, v192
	v_cvt_pk_bf16_f32 v127, v123, v193
	v_cvt_pk_bf16_f32 v128, v124, v194
	v_cvt_pk_bf16_f32 v129, v125, v195
	s_waitcnt lgkmcnt(0)
	v_max_f32_e32 v131, v131, v133
	ds_bpermute_b32 v133, v176, v131
	v_cvt_pk_bf16_f32 v122, v0, v164
	v_cvt_pk_bf16_f32 v123, v177, v179
	v_cvt_pk_bf16_f32 v124, v130, v132
	v_add_f32_e32 v130, 0x41000000, v165
	s_waitcnt lgkmcnt(0)
	v_max_f32_e32 v0, v131, v133
	v_mul_f32_e32 v0, 0x3e16c740, v0
	v_cmp_gt_f32_e32 vcc, v0, v130
	v_cvt_pk_bf16_f32 v125, v196, v166
	s_cbranch_vccz .LBB0_673
	s_nop 0
	v_cndmask_b32_e32 v169, v165, v0, vcc
	v_sub_f32_e32 v0, v165, v169
	v_exp_f32_e32 v0, v0
	v_mov_b32_e32 v165, v169
	v_mul_f32_e32 v161, v161, v0
	v_pk_mul_f32 v[104:105], v[104:105], v[0:1] op_sel_hi:[1,0]
	v_pk_mul_f32 v[102:103], v[102:103], v[0:1] op_sel_hi:[1,0]
	v_pk_mul_f32 v[100:101], v[100:101], v[0:1] op_sel_hi:[1,0]
	v_pk_mul_f32 v[98:99], v[98:99], v[0:1] op_sel_hi:[1,0]
	v_pk_mul_f32 v[96:97], v[96:97], v[0:1] op_sel_hi:[1,0]
	v_pk_mul_f32 v[94:95], v[94:95], v[0:1] op_sel_hi:[1,0]
	v_pk_mul_f32 v[92:93], v[92:93], v[0:1] op_sel_hi:[1,0]
	v_pk_mul_f32 v[90:91], v[90:91], v[0:1] op_sel_hi:[1,0]
.LBB0_673:
	v_fma_f32 v0, v106, s46, -v165
	v_exp_f32_e32 v106, v0
	v_fma_f32 v0, v107, s46, -v165
	v_exp_f32_e32 v130, v0
	v_fma_f32 v0, v108, s46, -v165
	v_exp_f32_e32 v107, v0
	v_fma_f32 v0, v109, s46, -v165
	v_exp_f32_e32 v131, v0
	v_fma_f32 v0, v110, s46, -v165
	v_exp_f32_e32 v108, v0
	v_fma_f32 v0, v111, s46, -v165
	v_exp_f32_e32 v110, v0
	v_fma_f32 v0, v112, s46, -v165
	v_exp_f32_e32 v109, v0
	v_fma_f32 v0, v113, s46, -v165
	v_exp_f32_e32 v111, v0
	v_add_f32_e32 v112, v106, v130
	v_add_f32_e32 v113, v107, v131
	v_cvt_pk_bf16_f32 v106, v106, v130
	v_cvt_pk_bf16_f32 v107, v107, v131
	s_nop 0
	v_add_f32_e32 v0, v112, v113
	v_add_f32_e32 v112, v108, v110
	v_add_f32_e32 v113, v109, v111
	v_add_f32_e32 v133, 0, v0
	v_add_f32_e32 v134, v112, v112
	v_add_f32_e32 v135, v112, v113
	v_fma_f32 v112, v115, s46, -v165
	v_exp_f32_e32 v136, v112
	v_fma_f32 v112, v116, s46, -v165
	v_fma_f32 v113, v119, s46, -v165
	v_fma_f32 v0, v114, s46, -v165
	v_exp_f32_e32 v137, v112
	v_fma_f32 v112, v117, s46, -v165
	v_exp_f32_e32 v114, v113
	v_fma_f32 v113, v120, s46, -v165
	v_exp_f32_e32 v0, v0
	v_exp_f32_e32 v164, v112
	v_fma_f32 v112, v118, s46, -v165
	v_exp_f32_e32 v134, v113
	v_fma_f32 v113, v121, s46, -v165
	v_exp_f32_e32 v112, v112
	v_exp_f32_e32 v132, v113
	v_add_f32_e32 v113, v0, v136
	v_add_f32_e32 v115, v137, v164
	v_add_f32_e32 v116, v112, v114
	v_add_f32_e32 v117, v113, v115
	v_add_f32_e32 v118, v134, v132
	v_add_f32_e32 v119, v135, v133
	v_cvt_pk_bf16_f32 v108, v108, v110
	v_cvt_pk_bf16_f32 v109, v109, v111
	v_cvt_pk_bf16_f32 v110, v0, v136
	v_cvt_pk_bf16_f32 v111, v137, v164
	v_cvt_pk_bf16_f32 v112, v112, v114
	s_nop 0
	v_add_f32_e32 v116, v116, v118
	v_add_f32_e32 v117, v117, v119
	s_nop 0
	v_add_f32_e32 v113, v116, v117
	ds_bpermute_b32 v115, v155, v113
	s_waitcnt lgkmcnt(0)
	v_add_f32_e32 v113, v113, v115
	ds_bpermute_b32 v115, v176, v113
	s_waitcnt lgkmcnt(0)
	v_add_f32_e32 v113, v113, v115
	v_add_f32_e32 v161, v161, v113
	v_cvt_pk_bf16_f32 v113, v134, v132
	ds_read_b64_tr_b16 v[116:117], v175 offset:18560
	ds_read_b64_tr_b16 v[114:115], v175 offset:17408
	ds_read_b64_tr_b16 v[118:119], v175 offset:17440
	ds_read_b64_tr_b16 v[120:121], v175 offset:18592
	s_waitcnt lgkmcnt(2)
	v_mfma_f32_16x16x32_bf16 v[86:89], v[114:117], v[126:129], v[86:89]
	v_mfma_f32_16x16x32_bf16 v[102:105], v[114:117], v[106:109], v[102:105]
	ds_read_b64_tr_b16 v[114:115], v175 offset:17472
	ds_read_b64_tr_b16 v[116:117], v175 offset:18624
	s_waitcnt lgkmcnt(0)
	v_mfma_f32_16x16x32_bf16 v[78:81], v[114:117], v[126:129], v[78:81]
	v_mfma_f32_16x16x32_bf16 v[94:97], v[114:117], v[106:109], v[94:97]
	ds_read_b64_tr_b16 v[114:115], v175 offset:17504
	ds_read_b64_tr_b16 v[116:117], v175 offset:18656
	v_mfma_f32_16x16x32_bf16 v[82:85], v[118:121], v[126:129], v[82:85]
	v_mfma_f32_16x16x32_bf16 v[98:101], v[118:121], v[106:109], v[98:101]
	s_waitcnt lgkmcnt(0)
	v_mfma_f32_16x16x32_bf16 v[74:77], v[114:117], v[126:129], v[74:77]
	v_mfma_f32_16x16x32_bf16 v[90:93], v[114:117], v[106:109], v[90:93]
	ds_read_b64_tr_b16 v[108:109], v175 offset:27776
	ds_read_b64_tr_b16 v[106:107], v175 offset:26624
	ds_read_b64_tr_b16 v[114:115], v175 offset:26656
	ds_read_b64_tr_b16 v[116:117], v175 offset:27808
	s_min_u32 s4, s44, s55
	s_lshl_b32 s4, s4, 6
	s_waitcnt lgkmcnt(2)
	v_mfma_f32_16x16x32_bf16 v[86:89], v[106:109], v[122:125], v[86:89]
	s_addk_i32 s4, 0xff00
	s_and_b64 s[48:49], s[40:41], exec
	s_cselect_b32 s58, 0xc0, s4
	v_mfma_f32_16x16x32_bf16 v[102:105], v[106:109], v[110:113], v[102:105]
	ds_read_b64_tr_b16 v[106:107], v175 offset:26688
	ds_read_b64_tr_b16 v[108:109], v175 offset:27840
	s_mul_i32 s52, s58, 0xc00
	s_lshl_b64 s[48:49], s[58:59], 11
	s_waitcnt lgkmcnt(0)
	v_mfma_f32_16x16x32_bf16 v[78:81], v[106:109], v[122:125], v[78:81]
	s_mul_hi_u32 s4, s58, 0xc00
	s_add_u32 s52, s42, s52
	s_addc_u32 s53, s43, s4
	v_mfma_f32_16x16x32_bf16 v[94:97], v[106:109], v[110:113], v[94:97]
	ds_read_b64_tr_b16 v[106:107], v175 offset:26720
	ds_read_b64_tr_b16 v[108:109], v175 offset:27872
	s_waitcnt lgkmcnt(0)
	s_barrier
	v_mfma_f32_16x16x32_bf16 v[74:77], v[106:109], v[122:125], v[74:77]
	s_waitcnt vmcnt(11)
	ds_write_b128 v170, v[62:65]
	s_waitcnt vmcnt(10)
	ds_write_b128 v171, v[66:69]
	s_waitcnt vmcnt(9)
	ds_write_b128 v172, v[70:73] offset:17408
	s_waitcnt lgkmcnt(0)
	v_mfma_f32_16x16x32_bf16 v[90:93], v[106:109], v[110:113], v[90:93]
	s_barrier
	ds_read_b128 v[106:109], v173
	ds_read_b128 v[134:137], v173 offset:8832
	v_mfma_f32_16x16x32_bf16 v[82:85], v[114:117], v[122:125], v[82:85]
	ds_read_b128 v[118:121], v174 offset:1088
	v_lshl_add_u64 v[62:63], v[146:147], 1, s[52:53]
	v_lshl_add_u64 v[66:67], v[148:149], 1, s[52:53]
	v_mfma_f32_16x16x32_bf16 v[98:101], v[114:117], v[110:113], v[98:101]
	ds_read_b128 v[114:117], v174
	v_lshl_add_u64 v[62:63], v[140:141], 1, v[62:63]
	v_lshl_add_u64 v[66:67], v[142:143], 1, v[66:67]
	s_waitcnt lgkmcnt(3)
	v_mfma_f32_16x16x32_bf16 v[110:113], v[106:109], v[2:5], 0
	v_lshl_add_u64 v[70:71], v[162:163], 0, s[48:49]
	global_load_dwordx4 v[62:65], v[62:63], off
	ds_read_b128 v[130:133], v174 offset:8704
	v_mfma_f32_16x16x32_bf16 v[106:109], v[106:109], v[14:17], 0
	global_load_dwordx4 v[66:69], v[66:67], off
	ds_read_b128 v[192:195], v174 offset:9792
	global_load_dwordx4 v[70:73], v[70:71], off
	s_waitcnt lgkmcnt(2)
	v_mfma_f32_16x16x32_bf16 v[110:113], v[114:117], v[6:9], v[110:113]
	v_mfma_f32_16x16x32_bf16 v[106:109], v[114:117], v[18:21], v[106:109]
	ds_read_b128 v[114:117], v173 offset:128
	s_waitcnt lgkmcnt(0)
	v_mfma_f32_16x16x32_bf16 v[122:125], v[114:117], v[10:13], v[110:113]
	s_nop 3
	ds_read_b128 v[110:113], v173 offset:1088
	s_nop 2
	s_nop 0
	v_mfma_f32_16x16x32_bf16 v[106:109], v[114:117], v[22:25], v[106:109]
	s_nop 0
	v_max_f32_e32 v0, v124, v125
	v_max3_f32 v0, v122, v123, v0
	s_waitcnt lgkmcnt(0)
	v_mfma_f32_16x16x32_bf16 v[114:117], v[110:113], v[2:5], 0
	v_mfma_f32_16x16x32_bf16 v[110:113], v[110:113], v[14:17], 0
	v_mfma_f32_16x16x32_bf16 v[114:117], v[118:121], v[6:9], v[114:117]
	v_mfma_f32_16x16x32_bf16 v[110:113], v[118:121], v[18:21], v[110:113]
	ds_read_b128 v[118:121], v173 offset:1216
	s_waitcnt lgkmcnt(0)
	v_mfma_f32_16x16x32_bf16 v[126:129], v[118:121], v[10:13], v[114:117]
	s_nop 3
	ds_read_b128 v[114:117], v173 offset:8704
	s_nop 2
	s_nop 0
	v_mfma_f32_16x16x32_bf16 v[110:113], v[118:121], v[22:25], v[110:113]
	s_nop 0
	v_max_f32_e32 v164, v128, v129
	v_max3_f32 v164, v126, v127, v164
	s_waitcnt lgkmcnt(0)
	v_mfma_f32_16x16x32_bf16 v[118:121], v[114:117], v[2:5], 0
	v_max3_f32 v0, v0, s51, v164
	v_mfma_f32_16x16x32_bf16 v[114:117], v[114:117], v[14:17], 0
	v_mfma_f32_16x16x32_bf16 v[118:121], v[130:133], v[6:9], v[118:121]
	v_mfma_f32_16x16x32_bf16 v[114:117], v[130:133], v[18:21], v[114:117]
	v_mfma_f32_16x16x32_bf16 v[130:133], v[134:137], v[10:13], v[118:121]
	s_nop 5
	ds_read_b128 v[118:121], v173 offset:9792
	v_mfma_f32_16x16x32_bf16 v[114:117], v[134:137], v[22:25], v[114:117]
	s_nop 1
	v_max_f32_e32 v164, v132, v133
	s_waitcnt lgkmcnt(0)
	v_mfma_f32_16x16x32_bf16 v[134:137], v[118:121], v[2:5], 0
	v_max3_f32 v164, v130, v131, v164
	v_mfma_f32_16x16x32_bf16 v[118:121], v[118:121], v[14:17], 0
	v_mfma_f32_16x16x32_bf16 v[134:137], v[192:195], v[6:9], v[134:137]
	v_mfma_f32_16x16x32_bf16 v[118:121], v[192:195], v[18:21], v[118:121]
	ds_read_b128 v[192:195], v173 offset:9920
	s_waitcnt lgkmcnt(0)
	v_mfma_f32_16x16x32_bf16 v[134:137], v[192:195], v[10:13], v[134:137]
	s_nop 7
	s_nop 1
	v_max_f32_e32 v166, v136, v137
	v_max3_f32 v166, v134, v135, v166
	v_max3_f32 v0, v0, v164, v166
	ds_bpermute_b32 v164, v155, v0
	v_mfma_f32_16x16x32_bf16 v[118:121], v[192:195], v[22:25], v[118:121]
	s_waitcnt lgkmcnt(0)
	v_max_f32_e32 v0, v0, v164
	ds_bpermute_b32 v164, v176, v0
	s_waitcnt lgkmcnt(0)
	v_max_f32_e32 v0, v0, v164
	v_mul_f32_e32 v0, 0x3e16c740, v0
	v_add_f32_e32 v164, 0x41000000, v168
	v_cmp_gt_f32_e32 vcc, v0, v164
	s_cbranch_vccz .LBB0_675
	s_nop 0
	v_cndmask_b32_e32 v166, v168, v0, vcc
	v_sub_f32_e32 v0, v168, v166
	v_exp_f32_e32 v0, v0
	v_mov_b32_e32 v167, v169
	v_mov_b32_e32 v165, v169
	v_mov_b32_e32 v168, v166
	v_mul_f32_e32 v160, v160, v0
	v_pk_mul_f32 v[88:89], v[88:89], v[0:1] op_sel_hi:[1,0]
	v_pk_mul_f32 v[86:87], v[86:87], v[0:1] op_sel_hi:[1,0]
	v_pk_mul_f32 v[84:85], v[84:85], v[0:1] op_sel_hi:[1,0]
	v_pk_mul_f32 v[82:83], v[82:83], v[0:1] op_sel_hi:[1,0]
	v_pk_mul_f32 v[80:81], v[80:81], v[0:1] op_sel_hi:[1,0]
	v_pk_mul_f32 v[78:79], v[78:79], v[0:1] op_sel_hi:[1,0]
	v_pk_mul_f32 v[76:77], v[76:77], v[0:1] op_sel_hi:[1,0]
	v_pk_mul_f32 v[74:75], v[74:75], v[0:1] op_sel_hi:[1,0]
	s_branch .LBB0_676

.LBB0_676:
	v_fma_f32 v0, v122, s46, -v168
	v_exp_f32_e32 v122, v0
	v_fma_f32 v0, v123, s46, -v168
	v_exp_f32_e32 v192, v0
	v_fma_f32 v0, v124, s46, -v168
	v_exp_f32_e32 v123, v0
	v_fma_f32 v0, v125, s46, -v168
	v_exp_f32_e32 v193, v0
	v_fma_f32 v0, v126, s46, -v168
	v_exp_f32_e32 v124, v0
	v_fma_f32 v0, v127, s46, -v168
	v_exp_f32_e32 v194, v0
	v_fma_f32 v0, v128, s46, -v168
	v_exp_f32_e32 v125, v0
	v_fma_f32 v0, v129, s46, -v168
	v_exp_f32_e32 v195, v0
	v_pk_add_f32 v[126:127], v[122:123], v[192:193]
	s_nop 0
	v_add_f32_e32 v0, v126, v127
	v_pk_add_f32 v[126:127], v[124:125], v[194:195]
	v_add_f32_e32 v169, 0, v0
	v_pk_add_f32 v[196:197], v[126:127], v[126:127] op_sel_hi:[0,1]
	v_fma_f32 v126, v131, s46, -v168
	v_exp_f32_e32 v164, v126
	v_fma_f32 v126, v132, s46, -v168
	v_exp_f32_e32 v177, v126
	v_fma_f32 v126, v133, s46, -v168
	v_exp_f32_e32 v179, v126
	v_fma_f32 v126, v134, s46, -v168
	v_fma_f32 v0, v130, s46, -v168
	v_exp_f32_e32 v130, v126
	v_fma_f32 v126, v135, s46, -v168
	v_exp_f32_e32 v132, v126
	v_fma_f32 v126, v136, s46, -v168
	v_exp_f32_e32 v0, v0
	v_exp_f32_e32 v196, v126
	v_fma_f32 v126, v137, s46, -v168
	v_exp_f32_e32 v168, v126
	v_add_f32_e32 v131, v0, v164
	v_add_f32_e32 v133, v177, v179
	v_pk_add_f32 v[126:127], v[130:131], v[132:133]
	v_pk_add_f32 v[128:129], v[196:197], v[168:169]
	s_nop 0
	v_pk_add_f32 v[126:127], v[126:127], v[128:129]
	s_nop 0
	v_add_f32_e32 v126, v126, v127
	ds_bpermute_b32 v127, v155, v126
	s_waitcnt lgkmcnt(0)
	v_add_f32_e32 v126, v126, v127
	ds_bpermute_b32 v127, v176, v126
	s_waitcnt lgkmcnt(0)
	v_add_f32_e32 v126, v126, v127
	v_add_f32_e32 v160, v160, v126
	v_max_f32_e32 v126, v108, v109
	v_max_f32_e32 v127, v112, v113
	v_max3_f32 v126, v106, v107, v126
	v_max3_f32 v127, v110, v111, v127
	v_max3_f32 v126, v126, s51, v127
	v_max_f32_e32 v127, v116, v117
	v_max_f32_e32 v128, v120, v121
	v_max3_f32 v127, v114, v115, v127
	v_max3_f32 v128, v118, v119, v128
	v_max3_f32 v131, v126, v127, v128
	ds_bpermute_b32 v133, v155, v131
	v_cvt_pk_bf16_f32 v126, v122, v192
	v_cvt_pk_bf16_f32 v127, v123, v193
	v_cvt_pk_bf16_f32 v128, v124, v194
	v_cvt_pk_bf16_f32 v129, v125, v195
	s_waitcnt lgkmcnt(0)
	v_max_f32_e32 v131, v131, v133
	ds_bpermute_b32 v133, v176, v131
	v_cvt_pk_bf16_f32 v122, v0, v164
	v_cvt_pk_bf16_f32 v123, v177, v179
	v_cvt_pk_bf16_f32 v124, v130, v132
	v_add_f32_e32 v130, 0x41000000, v165
	s_waitcnt lgkmcnt(0)
	v_max_f32_e32 v0, v131, v133
	v_mul_f32_e32 v0, 0x3e16c740, v0
	v_cmp_gt_f32_e32 vcc, v0, v130
	v_cvt_pk_bf16_f32 v125, v196, v168
	s_cbranch_vccz .LBB0_657
	s_nop 0
	v_cndmask_b32_e32 v167, v165, v0, vcc
	v_sub_f32_e32 v0, v165, v167
	v_exp_f32_e32 v0, v0
	v_mov_b32_e32 v165, v167
	v_mul_f32_e32 v161, v161, v0
	v_pk_mul_f32 v[104:105], v[104:105], v[0:1] op_sel_hi:[1,0]
	v_pk_mul_f32 v[102:103], v[102:103], v[0:1] op_sel_hi:[1,0]
	v_pk_mul_f32 v[100:101], v[100:101], v[0:1] op_sel_hi:[1,0]
	v_pk_mul_f32 v[98:99], v[98:99], v[0:1] op_sel_hi:[1,0]
	v_pk_mul_f32 v[96:97], v[96:97], v[0:1] op_sel_hi:[1,0]
	v_pk_mul_f32 v[94:95], v[94:95], v[0:1] op_sel_hi:[1,0]
	v_pk_mul_f32 v[92:93], v[92:93], v[0:1] op_sel_hi:[1,0]
	v_pk_mul_f32 v[90:91], v[90:91], v[0:1] op_sel_hi:[1,0]
	s_branch .LBB0_657

.LBB0_1075:
	s_barrier
	s_waitcnt vmcnt(7)
	ds_write_b128 v167, v[28:31]
	s_waitcnt vmcnt(6)
	ds_write_b128 v168, v[32:35]
	s_waitcnt vmcnt(5)
	ds_write_b128 v169, v[44:47] offset:17408
	s_waitcnt vmcnt(4)
	ds_write_b128 v170, v[48:51] offset:17408
	s_waitcnt lgkmcnt(0)
	s_barrier
	ds_read_b128 v[28:31], v171
	ds_read_b128 v[44:47], v171 offset:1088
	ds_read_b128 v[32:35], v172
	s_add_i32 s47, s45, -1
	ds_read_b128 v[48:51], v172 offset:1088
	s_min_u32 s4, s47, s44
	s_waitcnt lgkmcnt(3)
	v_mfma_f32_16x16x32_bf16 v[28:31], v[28:31], v[4:7], 0
	s_lshl_b32 s54, s4, 6
	s_cmp_lt_u32 s4, 4
	s_cselect_b64 s[48:49], -1, 0
	s_add_i32 s4, s54, 0xffffff00
	s_and_b64 s[52:53], s[48:49], exec
	s_waitcnt lgkmcnt(1)
	v_mfma_f32_16x16x32_bf16 v[128:131], v[32:35], v[8:11], v[28:31]
	s_cselect_b32 s58, s54, s4
	s_cselect_b32 s4, s27, s15
	s_cselect_b32 s54, s26, s14
	v_mfma_f32_16x16x32_bf16 v[28:31], v[44:47], v[4:7], 0
	ds_read_b128 v[44:47], v171 offset:8704
	s_lshl_b64 s[52:53], s[58:59], 11
	s_add_u32 s54, s54, s52
	s_addc_u32 s4, s4, s53
	s_waitcnt lgkmcnt(1)
	v_mfma_f32_16x16x32_bf16 v[124:127], v[48:51], v[8:11], v[28:31]
	ds_read_b128 v[48:51], v172 offset:8704
	s_and_b64 s[48:49], s[48:49], exec
	s_cselect_b32 s49, s36, s24
	s_cselect_b32 s48, s37, s25
	s_add_u32 s52, s49, s52
	s_addc_u32 s53, s48, s53
	s_add_u32 s48, s54, s40
	s_waitcnt lgkmcnt(1)
	v_mfma_f32_16x16x32_bf16 v[44:47], v[44:47], v[4:7], 0
	s_addc_u32 s49, s4, s41
	v_lshl_add_u64 v[2:3], v[152:153], 1, s[48:49]
	v_lshl_add_u64 v[32:33], v[154:155], 1, s[48:49]
	s_add_u32 s48, s52, s40
	v_lshl_add_u64 v[2:3], v[140:141], 1, v[2:3]
	v_lshl_add_u64 v[32:33], v[142:143], 1, v[32:33]
	s_addc_u32 s49, s53, s41
	global_load_dwordx4 v[28:31], v[2:3], off
	s_nop 0
	global_load_dwordx4 v[32:35], v[32:33], off
	v_lshl_add_u64 v[2:3], v[150:151], 1, s[48:49]
	s_waitcnt lgkmcnt(0)
	v_mfma_f32_16x16x32_bf16 v[120:123], v[48:51], v[8:11], v[44:47]
	v_lshl_add_u64 v[2:3], v[144:145], 1, v[2:3]
	ds_read_b128 v[116:119], v171 offset:9792
	ds_read_b128 v[132:135], v172 offset:9792
	v_lshl_add_u64 v[44:45], v[156:157], 1, s[48:49]
	v_lshl_add_u64 v[48:49], v[146:147], 1, v[44:45]
	global_load_dwordx4 v[44:47], v[2:3], off
	s_nop 0
	global_load_dwordx4 v[48:51], v[48:49], off
	s_waitcnt lgkmcnt(1)
	v_mfma_f32_16x16x32_bf16 v[116:119], v[116:119], v[4:7], 0
	s_nop 1
	v_max_f32_e32 v0, v130, v131
	s_waitcnt lgkmcnt(0)
	v_mfma_f32_16x16x32_bf16 v[116:119], v[132:135], v[8:11], v[116:119]
	s_nop 1
	v_max_f32_e32 v2, v126, v127
	v_max3_f32 v0, v128, v129, v0
	v_max3_f32 v2, v124, v125, v2
	v_max3_f32 v0, v0, s51, v2
	s_nop 1
	v_max_f32_e32 v2, v122, v123
	s_nop 1
	v_max_f32_e32 v3, v118, v119
	v_max3_f32 v2, v120, v121, v2
	v_max3_f32 v3, v116, v117, v3
	v_max3_f32 v0, v0, v2, v3
	ds_bpermute_b32 v2, v198, v0
	s_waitcnt lgkmcnt(0)
	v_max_f32_e32 v0, v0, v2
	ds_bpermute_b32 v2, v179, v0
	s_waitcnt lgkmcnt(0)
	v_max_f32_e32 v0, v0, v2
	v_mul_f32_e32 v0, 0x3e38aa3b, v0
	v_add_f32_e32 v2, 0x41000000, v193
	v_cmp_gt_f32_e32 vcc, v0, v2
	s_cbranch_vccz .LBB0_1077
	s_nop 0
	v_cndmask_b32_e32 v2, v193, v0, vcc
	v_sub_f32_e32 v0, v193, v2
	v_exp_f32_e32 v0, v0
	v_mov_b32_e32 v193, v2
	v_pk_mul_f32 v[114:115], v[114:115], v[0:1] op_sel_hi:[1,0]
	v_pk_mul_f32 v[112:113], v[112:113], v[0:1] op_sel_hi:[1,0]
	v_pk_mul_f32 v[106:107], v[106:107], v[0:1] op_sel_hi:[1,0]
	v_pk_mul_f32 v[104:105], v[104:105], v[0:1] op_sel_hi:[1,0]
	v_pk_mul_f32 v[98:99], v[98:99], v[0:1] op_sel_hi:[1,0]
	v_pk_mul_f32 v[96:97], v[96:97], v[0:1] op_sel_hi:[1,0]
	v_pk_mul_f32 v[90:91], v[90:91], v[0:1] op_sel_hi:[1,0]
	v_pk_mul_f32 v[88:89], v[88:89], v[0:1] op_sel_hi:[1,0]
	v_pk_mul_f32 v[82:83], v[82:83], v[0:1] op_sel_hi:[1,0]
	v_pk_mul_f32 v[80:81], v[80:81], v[0:1] op_sel_hi:[1,0]
	v_pk_mul_f32 v[74:75], v[74:75], v[0:1] op_sel_hi:[1,0]
	v_pk_mul_f32 v[72:73], v[72:73], v[0:1] op_sel_hi:[1,0]
	v_pk_mul_f32 v[66:67], v[66:67], v[0:1] op_sel_hi:[1,0]
	v_pk_mul_f32 v[64:65], v[64:65], v[0:1] op_sel_hi:[1,0]
	v_pk_mul_f32 v[62:63], v[62:63], v[0:1] op_sel_hi:[1,0]
	v_pk_mul_f32 v[60:61], v[60:61], v[0:1] op_sel_hi:[1,0]
	v_mul_f32_e32 v195, v195, v0
.LBB0_1077:
	v_fma_f32 v0, v128, s23, -v193
	v_exp_f32_e32 v3, v0
	v_fma_f32 v0, v129, s23, -v193
	v_exp_f32_e32 v128, v0
	v_fma_f32 v0, v130, s23, -v193
	v_exp_f32_e32 v129, v0
	v_fma_f32 v0, v131, s23, -v193
	v_exp_f32_e32 v130, v0
	v_add_f32_e32 v0, v3, v128
	v_add_f32_e32 v2, v129, v130
	v_add_f32_e32 v0, v0, v2
	v_fma_f32 v2, v124, s23, -v193
	v_exp_f32_e32 v124, v2
	v_fma_f32 v2, v125, s23, -v193
	v_exp_f32_e32 v125, v2
	v_fma_f32 v2, v126, s23, -v193
	v_exp_f32_e32 v126, v2
	v_fma_f32 v2, v127, s23, -v193
	v_exp_f32_e32 v127, v2
	v_add_f32_e32 v2, v124, v125
	v_add_f32_e32 v0, 0, v0
	v_add_f32_e32 v131, v126, v127
	v_add_f32_e32 v2, v2, v131
	v_add_f32_e32 v0, v2, v0
	v_fma_f32 v2, v120, s23, -v193
	v_exp_f32_e32 v131, v2
	v_fma_f32 v2, v121, s23, -v193
	v_exp_f32_e32 v132, v2
	v_fma_f32 v2, v122, s23, -v193
	v_exp_f32_e32 v133, v2
	v_fma_f32 v2, v123, s23, -v193
	v_exp_f32_e32 v134, v2
	v_add_f32_e32 v2, v131, v132
	v_add_f32_e32 v120, v133, v134
	v_add_f32_e32 v2, v2, v120
	v_add_f32_e32 v0, v2, v0
	v_fma_f32 v2, v116, s23, -v193
	v_exp_f32_e32 v135, v2
	v_fma_f32 v2, v117, s23, -v193
	v_exp_f32_e32 v136, v2
	v_fma_f32 v2, v118, s23, -v193
	v_exp_f32_e32 v137, v2
	v_fma_f32 v2, v119, s23, -v193
	v_exp_f32_e32 v119, v2
	v_add_f32_e32 v2, v135, v136
	v_cvt_pk_bf16_f32 v120, v3, v128
	v_cvt_pk_bf16_f32 v121, v129, v130
	v_add_f32_e32 v116, v137, v119
	v_add_f32_e32 v2, v2, v116
	v_cvt_pk_bf16_f32 v122, v124, v125
	v_cvt_pk_bf16_f32 v123, v126, v127
	v_cvt_pk_bf16_f32 v116, v131, v132
	v_cvt_pk_bf16_f32 v117, v133, v134
	v_cvt_pk_bf16_f32 v118, v135, v136
	v_cvt_pk_bf16_f32 v119, v137, v119
	ds_read_b128 v[124:127], v171 offset:128
	ds_read_b128 v[128:131], v173
	s_waitcnt lgkmcnt(1)
	v_mfma_f32_16x16x32_bf16 v[124:127], v[124:127], v[12:15], 0
	ds_read_b128 v[132:135], v173 offset:1088
	ds_read_b128 v[136:139], v173 offset:8704
	v_add_f32_e32 v0, v2, v0
	s_waitcnt lgkmcnt(2)
	v_mfma_f32_16x16x32_bf16 v[124:127], v[128:131], v[16:19], v[124:127]
	ds_read_b128 v[128:131], v171 offset:1216
	ds_bpermute_b32 v2, v198, v0
	ds_read_b128 v[200:203], v173 offset:9792
	s_waitcnt lgkmcnt(2)
	v_mfma_f32_16x16x32_bf16 v[128:131], v[128:131], v[12:15], 0
	s_nop 2
	s_nop 1
	v_max_f32_e32 v3, v126, v127
	v_mfma_f32_16x16x32_bf16 v[128:131], v[132:135], v[16:19], v[128:131]
	ds_read_b128 v[132:135], v171 offset:8832
	v_max3_f32 v3, v124, v125, v3
	s_waitcnt lgkmcnt(2)
	v_add_f32_e32 v0, v0, v2
	s_waitcnt lgkmcnt(0)
	v_mfma_f32_16x16x32_bf16 v[132:135], v[132:135], v[12:15], 0
	s_nop 1
	s_nop 1
	v_max_f32_e32 v196, v130, v131
	v_mfma_f32_16x16x32_bf16 v[132:135], v[136:139], v[16:19], v[132:135]
	ds_read_b128 v[136:139], v171 offset:9920
	v_max3_f32 v196, v128, v129, v196
	v_max3_f32 v3, v3, s51, v196
	s_waitcnt lgkmcnt(0)
	v_mfma_f32_16x16x32_bf16 v[136:139], v[136:139], v[12:15], 0
	s_nop 2
	s_nop 1
	v_max_f32_e32 v196, v134, v135
	v_mfma_f32_16x16x32_bf16 v[136:139], v[200:203], v[16:19], v[136:139]
	v_max3_f32 v196, v132, v133, v196
	ds_bpermute_b32 v2, v179, v0
	s_nop 5
	s_nop 1
	v_max_f32_e32 v197, v138, v139
	v_max3_f32 v197, v136, v137, v197
	v_max3_f32 v3, v3, v196, v197
	ds_bpermute_b32 v196, v198, v3
	s_waitcnt lgkmcnt(0)
	v_max_f32_e32 v3, v3, v196
	ds_bpermute_b32 v196, v179, v3
	s_waitcnt lgkmcnt(0)
	v_max_f32_e32 v3, v3, v196
	v_mul_f32_e32 v3, 0x3e38aa3b, v3
	v_add_f32_e32 v196, 0x41000000, v161
	v_cmp_gt_f32_e32 vcc, v3, v196
	s_cbranch_vccz .LBB0_1079
	s_nop 0
	v_cndmask_b32_e32 v3, v161, v3, vcc
	v_sub_f32_e32 v161, v161, v3
	v_exp_f32_e32 v196, v161
	v_mov_b32_e32 v161, v3
	v_pk_mul_f32 v[110:111], v[110:111], v[196:197] op_sel_hi:[1,0]
	v_pk_mul_f32 v[108:109], v[108:109], v[196:197] op_sel_hi:[1,0]
	v_pk_mul_f32 v[102:103], v[102:103], v[196:197] op_sel_hi:[1,0]
	v_pk_mul_f32 v[100:101], v[100:101], v[196:197] op_sel_hi:[1,0]
	v_pk_mul_f32 v[94:95], v[94:95], v[196:197] op_sel_hi:[1,0]
	v_pk_mul_f32 v[92:93], v[92:93], v[196:197] op_sel_hi:[1,0]
	v_pk_mul_f32 v[86:87], v[86:87], v[196:197] op_sel_hi:[1,0]
	v_pk_mul_f32 v[84:85], v[84:85], v[196:197] op_sel_hi:[1,0]
	v_pk_mul_f32 v[78:79], v[78:79], v[196:197] op_sel_hi:[1,0]
	v_pk_mul_f32 v[76:77], v[76:77], v[196:197] op_sel_hi:[1,0]
	v_pk_mul_f32 v[70:71], v[70:71], v[196:197] op_sel_hi:[1,0]
	v_pk_mul_f32 v[68:69], v[68:69], v[196:197] op_sel_hi:[1,0]
	v_pk_mul_f32 v[58:59], v[58:59], v[196:197] op_sel_hi:[1,0]
	v_pk_mul_f32 v[56:57], v[56:57], v[196:197] op_sel_hi:[1,0]
	v_pk_mul_f32 v[54:55], v[54:55], v[196:197] op_sel_hi:[1,0]
	v_pk_mul_f32 v[52:53], v[52:53], v[196:197] op_sel_hi:[1,0]
	v_mul_f32_e32 v194, v194, v196
.LBB0_1079:
	v_add_f32_e32 v0, v0, v2
	v_fma_f32 v2, v124, s23, -v161
	v_exp_f32_e32 v124, v2
	v_fma_f32 v2, v125, s23, -v161
	v_exp_f32_e32 v125, v2
	v_fma_f32 v2, v126, s23, -v161
	v_exp_f32_e32 v126, v2
	v_fma_f32 v2, v127, s23, -v161
	v_exp_f32_e32 v127, v2
	v_add_f32_e32 v2, v124, v125
	v_add_f32_e32 v0, v195, v0
	v_add_f32_e32 v3, v126, v127
	v_add_f32_e32 v2, v2, v3
	v_fma_f32 v3, v128, s23, -v161
	v_exp_f32_e32 v195, v3
	v_fma_f32 v3, v129, s23, -v161
	v_exp_f32_e32 v196, v3
	v_fma_f32 v3, v130, s23, -v161
	v_exp_f32_e32 v197, v3
	v_fma_f32 v3, v131, s23, -v161
	v_exp_f32_e32 v131, v3
	v_add_f32_e32 v3, v195, v196
	v_add_f32_e32 v2, 0, v2
	v_add_f32_e32 v128, v197, v131
	v_add_f32_e32 v3, v3, v128
	v_add_f32_e32 v2, v3, v2
	v_fma_f32 v3, v132, s23, -v161
	v_exp_f32_e32 v132, v3
	v_fma_f32 v3, v133, s23, -v161
	v_exp_f32_e32 v133, v3
	v_fma_f32 v3, v134, s23, -v161
	v_exp_f32_e32 v134, v3
	v_fma_f32 v3, v135, s23, -v161
	v_exp_f32_e32 v135, v3
	v_add_f32_e32 v3, v132, v133
	v_add_f32_e32 v128, v134, v135
	v_add_f32_e32 v3, v3, v128
	v_add_f32_e32 v2, v3, v2
	v_fma_f32 v3, v136, s23, -v161
	v_exp_f32_e32 v136, v3
	v_fma_f32 v3, v137, s23, -v161
	v_exp_f32_e32 v137, v3
	v_fma_f32 v3, v138, s23, -v161
	v_exp_f32_e32 v138, v3
	v_fma_f32 v3, v139, s23, -v161
	v_exp_f32_e32 v139, v3
	v_add_f32_e32 v3, v136, v137
	v_add_f32_e32 v128, v138, v139
	v_add_f32_e32 v3, v3, v128
	v_add_f32_e32 v2, v3, v2
	ds_bpermute_b32 v3, v198, v2
	v_cvt_pk_bf16_f32 v128, v124, v125
	v_cvt_pk_bf16_f32 v129, v126, v127
	v_cvt_pk_bf16_f32 v130, v195, v196
	v_cvt_pk_bf16_f32 v131, v197, v131
	s_waitcnt lgkmcnt(0)
	v_add_f32_e32 v2, v2, v3
	ds_bpermute_b32 v3, v179, v2
	v_cvt_pk_bf16_f32 v124, v132, v133
	v_cvt_pk_bf16_f32 v125, v134, v135
	v_cvt_pk_bf16_f32 v126, v136, v137
	v_cvt_pk_bf16_f32 v127, v138, v139
	ds_read_b64_tr_b16 v[134:135], v174 offset:18560
	ds_read_b64_tr_b16 v[132:133], v174 offset:17408
	ds_read_b64_tr_b16 v[136:137], v174 offset:17440
	ds_read_b64_tr_b16 v[138:139], v174 offset:18592
	s_waitcnt lgkmcnt(2)
	v_mfma_f32_16x16x32_bf16 v[112:115], v[132:135], v[120:123], v[112:115]
	v_mfma_f32_16x16x32_bf16 v[108:111], v[132:135], v[128:131], v[108:111]
	ds_read_b64_tr_b16 v[132:133], v174 offset:17472
	ds_read_b64_tr_b16 v[134:135], v174 offset:18624
	s_waitcnt lgkmcnt(0)
	v_mfma_f32_16x16x32_bf16 v[96:99], v[132:135], v[120:123], v[96:99]
	v_mfma_f32_16x16x32_bf16 v[92:95], v[132:135], v[128:131], v[92:95]
	ds_read_b64_tr_b16 v[132:133], v174 offset:17504
	ds_read_b64_tr_b16 v[134:135], v174 offset:18656
	v_mfma_f32_16x16x32_bf16 v[104:107], v[136:139], v[120:123], v[104:107]
	v_mfma_f32_16x16x32_bf16 v[100:103], v[136:139], v[128:131], v[100:103]
	s_waitcnt lgkmcnt(0)
	v_mfma_f32_16x16x32_bf16 v[136:139], v[132:135], v[120:123], v[88:91]
	v_mfma_f32_16x16x32_bf16 v[132:135], v[132:135], v[128:131], v[84:87]
	s_nop 2
	ds_read_b64_tr_b16 v[84:85], v175 offset:17408
	ds_read_b64_tr_b16 v[86:87], v175 offset:18560
	s_waitcnt lgkmcnt(0)
	v_mfma_f32_16x16x32_bf16 v[204:207], v[84:87], v[128:131], v[76:79]
	s_nop 2
	ds_read_b64_tr_b16 v[76:77], v176 offset:17408
	ds_read_b64_tr_b16 v[78:79], v176 offset:18560
	s_waitcnt lgkmcnt(0)
	v_mfma_f32_16x16x32_bf16 v[208:211], v[76:79], v[128:131], v[68:71]
	s_nop 2
	ds_read_b64_tr_b16 v[68:69], v177 offset:17408
	ds_read_b64_tr_b16 v[70:71], v177 offset:18560
	s_waitcnt lgkmcnt(0)
	v_mfma_f32_16x16x32_bf16 v[216:219], v[68:71], v[128:131], v[56:59]
	s_nop 2
	ds_read_b64_tr_b16 v[56:57], v192 offset:17408
	ds_read_b64_tr_b16 v[58:59], v192 offset:18560
	v_mfma_f32_16x16x32_bf16 v[200:203], v[84:87], v[120:123], v[80:83]
	v_mfma_f32_16x16x32_bf16 v[72:75], v[76:79], v[120:123], v[72:75]
	v_mfma_f32_16x16x32_bf16 v[212:215], v[68:71], v[120:123], v[64:67]
	s_waitcnt lgkmcnt(0)
	v_mfma_f32_16x16x32_bf16 v[120:123], v[56:59], v[120:123], v[60:63]
	v_mfma_f32_16x16x32_bf16 v[128:131], v[56:59], v[128:131], v[52:55]
	s_min_u32 s4, s45, s44
	s_nop 1
	ds_read_b64_tr_b16 v[54:55], v174 offset:27776
	ds_read_b64_tr_b16 v[52:53], v174 offset:26624
	ds_read_b64_tr_b16 v[56:57], v174 offset:26656
	ds_read_b64_tr_b16 v[58:59], v174 offset:27808
	s_lshl_b32 s54, s4, 6
	s_cmp_lt_u32 s4, 4
	s_cselect_b64 s[48:49], -1, 0
	s_add_i32 s4, s54, 0xffffff00
	s_and_b64 s[52:53], s[48:49], exec
	s_cselect_b32 s58, s54, s4
	s_cselect_b32 s4, s27, s15
	s_cselect_b32 s54, s26, s14
	s_lshl_b64 s[52:53], s[58:59], 11
	s_add_u32 s54, s54, s52
	s_addc_u32 s4, s4, s53
	s_and_b64 s[48:49], s[48:49], exec
	s_waitcnt lgkmcnt(2)
	v_mfma_f32_16x16x32_bf16 v[68:71], v[52:55], v[116:119], v[112:115]
	s_cselect_b32 s49, s36, s24
	s_cselect_b32 s48, s37, s25
	s_add_u32 s52, s49, s52
	v_mfma_f32_16x16x32_bf16 v[80:83], v[52:55], v[124:127], v[108:111]
	ds_read_b64_tr_b16 v[52:53], v174 offset:26688
	ds_read_b64_tr_b16 v[54:55], v174 offset:27840
	s_addc_u32 s53, s48, s53
	s_add_u32 s48, s54, s40
	s_waitcnt lgkmcnt(2)
	v_mfma_f32_16x16x32_bf16 v[64:67], v[56:59], v[116:119], v[104:107]
	s_addc_u32 s49, s4, s41
	v_mfma_f32_16x16x32_bf16 v[76:79], v[56:59], v[124:127], v[100:103]
	ds_read_b64_tr_b16 v[56:57], v174 offset:26720
	ds_read_b64_tr_b16 v[58:59], v174 offset:27872
	ds_read_b64_tr_b16 v[60:61], v175 offset:26624
	ds_read_b64_tr_b16 v[62:63], v175 offset:27776
	ds_read_b64_tr_b16 v[100:101], v176 offset:26624
	ds_read_b64_tr_b16 v[102:103], v176 offset:27776
	s_waitcnt lgkmcnt(6)
	v_mfma_f32_16x16x32_bf16 v[84:87], v[52:55], v[116:119], v[96:99]
	v_mfma_f32_16x16x32_bf16 v[88:91], v[52:55], v[124:127], v[92:95]
	s_waitcnt lgkmcnt(2)
	v_mfma_f32_16x16x32_bf16 v[92:95], v[60:63], v[116:119], v[200:203]
	v_mfma_f32_16x16x32_bf16 v[96:99], v[60:63], v[124:127], v[204:207]
	s_waitcnt lgkmcnt(0)
	v_mfma_f32_16x16x32_bf16 v[60:63], v[100:103], v[116:119], v[72:75]
	v_mfma_f32_16x16x32_bf16 v[72:75], v[100:103], v[124:127], v[208:211]
	ds_read_b64_tr_b16 v[100:101], v177 offset:26624
	ds_read_b64_tr_b16 v[102:103], v177 offset:27776
	ds_read_b64_tr_b16 v[104:105], v192 offset:26624
	ds_read_b64_tr_b16 v[106:107], v192 offset:27776
	s_waitcnt lgkmcnt(0)
	s_barrier
	s_waitcnt vmcnt(7)
	ds_write_b128 v167, v[24:27]
	s_waitcnt vmcnt(6)
	ds_write_b128 v168, v[20:23]
	s_waitcnt vmcnt(5)
	ds_write_b128 v169, v[36:39] offset:17408
	s_waitcnt vmcnt(4)
	ds_write_b128 v170, v[40:43] offset:17408
	v_lshl_add_u64 v[20:21], v[152:153], 1, s[48:49]
	v_lshl_add_u64 v[20:21], v[140:141], 1, v[20:21]
	s_waitcnt lgkmcnt(0)
	s_barrier
	global_load_dwordx4 v[24:27], v[20:21], off
	v_lshl_add_u64 v[20:21], v[154:155], 1, s[48:49]
	s_add_u32 s48, s52, s40
	s_addc_u32 s49, s53, s41
	v_lshl_add_u64 v[36:37], v[150:151], 1, s[48:49]
	v_lshl_add_u64 v[40:41], v[156:157], 1, s[48:49]
	v_lshl_add_u64 v[20:21], v[142:143], 1, v[20:21]
	v_lshl_add_u64 v[36:37], v[144:145], 1, v[36:37]
	v_lshl_add_u64 v[40:41], v[146:147], 1, v[40:41]
	global_load_dwordx4 v[20:23], v[20:21], off
	v_mfma_f32_16x16x32_bf16 v[52:55], v[56:59], v[116:119], v[136:139]
	global_load_dwordx4 v[36:39], v[36:37], off
	s_nop 0
	global_load_dwordx4 v[40:43], v[40:41], off
	v_mfma_f32_16x16x32_bf16 v[108:111], v[100:103], v[116:119], v[212:215]
	v_mfma_f32_16x16x32_bf16 v[112:115], v[100:103], v[124:127], v[216:219]
	v_mfma_f32_16x16x32_bf16 v[100:103], v[104:107], v[116:119], v[120:123]
	ds_read_b128 v[116:119], v171
	s_nop 1
	ds_read_b128 v[120:123], v172
	s_waitcnt lgkmcnt(1)
	v_mfma_f32_16x16x32_bf16 v[116:119], v[116:119], v[4:7], 0
	s_waitcnt lgkmcnt(0)
	v_mfma_f32_16x16x32_bf16 v[116:119], v[120:123], v[8:11], v[116:119]
	ds_read_b128 v[120:123], v171 offset:1088
	v_mfma_f32_16x16x32_bf16 v[56:59], v[56:59], v[124:127], v[132:135]
	v_mfma_f32_16x16x32_bf16 v[104:107], v[104:107], v[124:127], v[128:131]
	ds_read_b128 v[124:127], v172 offset:1088
	s_nop 0
	ds_read_b128 v[132:135], v172 offset:9792
	s_waitcnt lgkmcnt(2)
	v_mfma_f32_16x16x32_bf16 v[120:123], v[120:123], v[4:7], 0
	ds_read_b128 v[128:131], v172 offset:8704
	s_waitcnt lgkmcnt(2)
	v_mfma_f32_16x16x32_bf16 v[120:123], v[124:127], v[8:11], v[120:123]
	ds_read_b128 v[124:127], v171 offset:8704
	s_waitcnt lgkmcnt(0)
	v_mfma_f32_16x16x32_bf16 v[124:127], v[124:127], v[4:7], 0
	v_mfma_f32_16x16x32_bf16 v[124:127], v[128:131], v[8:11], v[124:127]
	ds_read_b128 v[128:131], v171 offset:9792
	s_waitcnt lgkmcnt(0)
	v_mfma_f32_16x16x32_bf16 v[128:131], v[128:131], v[4:7], 0
	v_mfma_f32_16x16x32_bf16 v[128:131], v[132:135], v[8:11], v[128:131]
	s_nop 1
	v_max_f32_e32 v132, v118, v119
	s_nop 1
	v_max_f32_e32 v133, v122, v123
	v_max3_f32 v132, v116, v117, v132
	v_max3_f32 v133, v120, v121, v133
	v_max3_f32 v132, v132, s51, v133
	s_nop 1
	v_max_f32_e32 v133, v126, v127
	s_nop 1
	v_max_f32_e32 v134, v130, v131
	v_max3_f32 v133, v124, v125, v133
	v_max3_f32 v134, v128, v129, v134
	v_max3_f32 v132, v132, v133, v134
	ds_bpermute_b32 v133, v198, v132
	s_waitcnt lgkmcnt(0)
	v_max_f32_e32 v132, v132, v133
	ds_bpermute_b32 v133, v179, v132
	s_waitcnt lgkmcnt(0)
	v_max_f32_e32 v132, v132, v133
	v_mul_f32_e32 v132, 0x3e38aa3b, v132
	v_add_f32_e32 v133, 0x41000000, v193
	v_cmp_gt_f32_e32 vcc, v132, v133
	s_cbranch_vccz .LBB0_1081
	s_nop 0
	v_cndmask_b32_e32 v133, v193, v132, vcc
	v_sub_f32_e32 v132, v193, v133
	v_exp_f32_e32 v132, v132
	v_mov_b32_e32 v193, v133
	v_pk_mul_f32 v[70:71], v[70:71], v[132:133] op_sel_hi:[1,0]
	v_pk_mul_f32 v[68:69], v[68:69], v[132:133] op_sel_hi:[1,0]
	v_pk_mul_f32 v[66:67], v[66:67], v[132:133] op_sel_hi:[1,0]
	v_pk_mul_f32 v[64:65], v[64:65], v[132:133] op_sel_hi:[1,0]
	v_pk_mul_f32 v[86:87], v[86:87], v[132:133] op_sel_hi:[1,0]
	v_pk_mul_f32 v[84:85], v[84:85], v[132:133] op_sel_hi:[1,0]
	v_pk_mul_f32 v[54:55], v[54:55], v[132:133] op_sel_hi:[1,0]
	v_pk_mul_f32 v[52:53], v[52:53], v[132:133] op_sel_hi:[1,0]
	v_pk_mul_f32 v[94:95], v[94:95], v[132:133] op_sel_hi:[1,0]
	v_pk_mul_f32 v[92:93], v[92:93], v[132:133] op_sel_hi:[1,0]
	v_pk_mul_f32 v[62:63], v[62:63], v[132:133] op_sel_hi:[1,0]
	v_pk_mul_f32 v[60:61], v[60:61], v[132:133] op_sel_hi:[1,0]
	v_pk_mul_f32 v[110:111], v[110:111], v[132:133] op_sel_hi:[1,0]
	v_pk_mul_f32 v[108:109], v[108:109], v[132:133] op_sel_hi:[1,0]
	v_pk_mul_f32 v[102:103], v[102:103], v[132:133] op_sel_hi:[1,0]
	v_pk_mul_f32 v[100:101], v[100:101], v[132:133] op_sel_hi:[1,0]
	v_mul_f32_e32 v0, v0, v132
	v_xor_b32_e32 v132, 0x80000000, v133
	s_branch .LBB0_1082

.LBB0_1082:
	v_add_f32_e32 v2, v2, v3
	v_fmamk_f32 v3, v116, 0x3e38aa3b, v132
	v_exp_f32_e32 v116, v3
	v_fmamk_f32 v3, v117, 0x3e38aa3b, v132
	v_exp_f32_e32 v117, v3
	v_fmamk_f32 v3, v118, 0x3e38aa3b, v132
	v_exp_f32_e32 v118, v3
	v_fmamk_f32 v3, v119, 0x3e38aa3b, v132
	v_exp_f32_e32 v119, v3
	v_add_f32_e32 v3, v116, v117
	v_fmamk_f32 v120, v120, 0x3e38aa3b, v132
	v_add_f32_e32 v2, v194, v2
	v_add_f32_e32 v133, v118, v119
	v_add_f32_e32 v3, v3, v133
	v_exp_f32_e32 v133, v120
	v_fmamk_f32 v120, v121, 0x3e38aa3b, v132
	v_exp_f32_e32 v134, v120
	v_fmamk_f32 v120, v122, 0x3e38aa3b, v132
	v_exp_f32_e32 v135, v120
	v_fmamk_f32 v120, v123, 0x3e38aa3b, v132
	v_exp_f32_e32 v123, v120
	v_add_f32_e32 v120, v133, v134
	v_add_f32_e32 v3, 0, v3
	v_add_f32_e32 v121, v135, v123
	v_add_f32_e32 v120, v120, v121
	v_add_f32_e32 v3, v120, v3
	v_fmamk_f32 v120, v124, 0x3e38aa3b, v132
	v_exp_f32_e32 v124, v120
	v_fmamk_f32 v120, v125, 0x3e38aa3b, v132
	v_exp_f32_e32 v125, v120
	v_fmamk_f32 v120, v126, 0x3e38aa3b, v132
	v_exp_f32_e32 v126, v120
	v_fmamk_f32 v120, v127, 0x3e38aa3b, v132
	v_exp_f32_e32 v127, v120
	v_add_f32_e32 v120, v124, v125
	v_add_f32_e32 v121, v126, v127
	v_add_f32_e32 v120, v120, v121
	v_add_f32_e32 v3, v120, v3
	v_fmamk_f32 v120, v128, 0x3e38aa3b, v132
	v_exp_f32_e32 v128, v120
	v_fmamk_f32 v120, v129, 0x3e38aa3b, v132
	v_exp_f32_e32 v129, v120
	v_fmamk_f32 v120, v130, 0x3e38aa3b, v132
	v_fmac_f32_e32 v132, 0x3e38aa3b, v131
	v_exp_f32_e32 v130, v120
	v_exp_f32_e32 v131, v132
	v_add_f32_e32 v120, v128, v129
	v_add_f32_e32 v121, v130, v131
	v_add_f32_e32 v120, v120, v121
	v_add_f32_e32 v3, v120, v3
	ds_bpermute_b32 v120, v198, v3
	s_waitcnt lgkmcnt(0)
	v_add_f32_e32 v3, v3, v120
	v_cvt_pk_bf16_f32 v120, v116, v117
	v_cvt_pk_bf16_f32 v121, v118, v119
	v_cvt_pk_bf16_f32 v122, v133, v134
	v_cvt_pk_bf16_f32 v123, v135, v123
	v_cvt_pk_bf16_f32 v116, v124, v125
	v_cvt_pk_bf16_f32 v117, v126, v127
	v_cvt_pk_bf16_f32 v118, v128, v129
	v_cvt_pk_bf16_f32 v119, v130, v131
	ds_read_b128 v[124:127], v171 offset:128
	ds_read_b128 v[128:131], v173
	s_waitcnt lgkmcnt(1)
	v_mfma_f32_16x16x32_bf16 v[124:127], v[124:127], v[12:15], 0
	ds_read_b128 v[132:135], v173 offset:1088
	ds_read_b128 v[136:139], v173 offset:8704
	ds_bpermute_b32 v194, v179, v3
	s_waitcnt lgkmcnt(3)
	v_mfma_f32_16x16x32_bf16 v[124:127], v[128:131], v[16:19], v[124:127]
	ds_read_b128 v[128:131], v171 offset:1216
	ds_read_b128 v[200:203], v173 offset:9792
	s_waitcnt lgkmcnt(1)
	v_mfma_f32_16x16x32_bf16 v[128:131], v[128:131], v[12:15], 0
	s_nop 3
	s_nop 1
	v_max_f32_e32 v195, v126, v127
	v_mfma_f32_16x16x32_bf16 v[128:131], v[132:135], v[16:19], v[128:131]
	ds_read_b128 v[132:135], v171 offset:8832
	v_max3_f32 v195, v124, v125, v195
	s_waitcnt lgkmcnt(0)
	v_mfma_f32_16x16x32_bf16 v[132:135], v[132:135], v[12:15], 0
	s_nop 3
	s_nop 1
	v_max_f32_e32 v196, v130, v131
	v_mfma_f32_16x16x32_bf16 v[132:135], v[136:139], v[16:19], v[132:135]
	ds_read_b128 v[136:139], v171 offset:9920
	v_max3_f32 v196, v128, v129, v196
	v_max3_f32 v195, v195, s51, v196
	s_waitcnt lgkmcnt(0)
	v_mfma_f32_16x16x32_bf16 v[136:139], v[136:139], v[12:15], 0
	s_nop 2
	s_nop 1
	v_max_f32_e32 v196, v134, v135
	v_mfma_f32_16x16x32_bf16 v[136:139], v[200:203], v[16:19], v[136:139]
	v_max3_f32 v196, v132, v133, v196
	s_nop 6
	s_nop 1
	v_max_f32_e32 v197, v138, v139
	v_max3_f32 v197, v136, v137, v197
	v_max3_f32 v195, v195, v196, v197
	ds_bpermute_b32 v196, v198, v195
	s_waitcnt lgkmcnt(0)
	v_max_f32_e32 v195, v195, v196
	ds_bpermute_b32 v196, v179, v195
	s_waitcnt lgkmcnt(0)
	v_max_f32_e32 v195, v195, v196
	v_mul_f32_e32 v195, 0x3e38aa3b, v195
	v_add_f32_e32 v196, 0x41000000, v161
	v_cmp_gt_f32_e32 vcc, v195, v196
	s_cbranch_vccnz .LBB0_1073
	v_xor_b32_e32 v196, 0x80000000, v161
	s_branch .LBB0_1074
